# fuse F2 causal conv+SiLU gate into F1 GEMM epilogue (DPP row shifts), W_up rows interleaved gate/val per tile in PREP, F2 slot only fixes band rows 0,1 from halo buffer
# speedup vs baseline: 1.1300x; 1.0621x over previous
; __device__ __forceinline__ void conv_phase(const Params& p, int layer) {
;     ...
;     for (size_t task = gtid; task < ntask; task += nth) {
;         const int cgp = (int)(task % 352), rc = (int)(task / 352), f = cgp * 8, r0 = rc * 16;
;         float wg[3][8], wv[3][8], bg[8], bv[8];
; #pragma unroll
;         for (int jj = 0; jj < 3; ++jj)
; #pragma unroll
;             for (int hlf = 0; hlf < 2; ++hlf) {
;                 const f32x4 a = *(const f32x4*)(cw + jj * 5632 + f + hlf * 4), c = *(const f32x4*)(cw + jj * 5632 + DFF + f + hlf * 4);
; #pragma unroll
;                 for (int e = 0; e < 4; ++e) { wg[jj][hlf * 4 + e] = a[e]; wv[jj][hlf * 4 + e] = c[e]; }
;             }
; #pragma unroll
;         for (int hlf = 0; hlf < 2; ++hlf) {
;             const f32x4 a = *(const f32x4*)(cb + f + hlf * 4), c = *(const f32x4*)(cb + DFF + f + hlf * 4);
; #pragma unroll
;             for (int e = 0; e < 4; ++e) { bg[hlf * 4 + e] = a[e]; bv[hlf * 4 + e] = c[e]; }
;         }
;         float g2[8], g1[8], v2[8], v1[8];
; #pragma unroll
;         for (int e = 0; e < 8; ++e) { g2[e] = 0.f; g1[e] = 0.f; v2[e] = 0.f; v1[e] = 0.f; }
;         if ((r0 & 2047) != 0) {
;             unpack8(*(const u32x4*)(u + (size_t)(r0 - 2) * 5632 + f), g2); unpack8(*(const u32x4*)(u + (size_t)(r0 - 1) * 5632 + f), g1);
;             unpack8(*(const u32x4*)(u + (size_t)(r0 - 2) * 5632 + DFF + f), v2); unpack8(*(const u32x4*)(u + (size_t)(r0 - 1) * 5632 + DFF + f), v1);
;         }
; #pragma unroll 1
;         for (int i0 = 0; i0 < 16; i0 += 4) {
;             u32x4 lg[4], lv[4];
; #pragma unroll
;             for (int i = 0; i < 4; ++i) { const size_t ro = (size_t)(r0 + i0 + i) * 5632; lg[i] = *(const u32x4*)(u + ro + f); lv[i] = *(const u32x4*)(u + ro + DFF + f); }
; #pragma unroll
;             for (int i = 0; i < 4; ++i) {
;                 float g0[8], v0[8], o[8];
;                 unpack8(lg[i], g0); unpack8(lv[i], v0);
; #pragma unroll
;                 for (int e = 0; e < 8; ++e) {
;                     const float G = wg[0][e] * g2[e] + wg[1][e] * g1[e] + wg[2][e] * g0[e] + bg[e];
;                     const float V = wv[0][e] * v2[e] + wv[1][e] * v1[e] + wv[2][e] * v0[e] + bv[e];
;                     o[e] = G * sigmoidf_(G) * V;
;                     g2[e] = g1[e]; g1[e] = g0[e]; v2[e] = v1[e]; v1[e] = v0[e];
;                 }
.LBB0_472:
	s_and_b64 vcc, exec, s[0:1]
	s_cbranch_vccz .LBB0_482
	v_readlane_b32 s0, v253, 12
	s_cmp_eq_u32 s0, 7
	s_cbranch_scc0 .LBB0_482
	v_mov_b32_e32 v0, v226
	v_readlane_b32 s0, v250, 40
	v_readlane_b32 s1, v250, 41
	v_ashrrev_i32_e32 v1, 31, v0
	s_waitcnt vmcnt(0)
	v_lshl_add_u64 v[96:97], s[0:1], 0, v[0:1]
	s_mov_b64 s[0:1], 0x2c000
	v_cmp_gt_u64_e32 vcc, s[0:1], v[96:97]
	s_and_saveexec_b64 s[0:1], vcc
	s_cbranch_execz .LBB0_481
	s_mov_b64 s[2:3], 0
.LBB0_476:
	s_mov_b32 s4, 0xba2e8ba3
	v_mul_hi_u32 v65, v96, s4
	v_lshrrev_b32_e32 v98, 8, v65
	v_mul_u32_u24_e32 v0, 0x160, v98
	v_sub_u32_e32 v0, v96, v0
	v_lshlrev_b32_e32 v196, 3, v0
	v_lshlrev_b64 v[144:145], 2, v[196:197]
	v_lshlrev_b64 v[146:147], 1, v[196:197]
	v_and_b32_e32 v99, 31, v98
	s_waitcnt vmcnt(0)
	v_readlane_b32 s4, v253, 32
	v_readlane_b32 s5, v253, 33
	s_nop 3
	v_lshl_add_u64 v[66:67], s[4:5], 0, v[144:145]
	s_nop 1
	global_load_dwordx4 v[0:3], v[66:67], off offset:16
	global_load_dwordx4 v[4:7], v[66:67], off
	s_nop 1
	v_readlane_b32 s4, v253, 24
	v_readlane_b32 s5, v253, 25
	s_nop 3
	v_lshl_add_u64 v[66:67], s[4:5], 0, v[144:145]
	s_nop 1
	global_load_dwordx4 v[8:11], v[66:67], off offset:16
	global_load_dwordx4 v[12:15], v[66:67], off
	s_nop 1
	v_readlane_b32 s4, v253, 26
	v_readlane_b32 s5, v253, 27
	s_nop 3
	v_lshl_add_u64 v[66:67], s[4:5], 0, v[144:145]
	s_nop 1
	global_load_dwordx4 v[16:19], v[66:67], off offset:16
	global_load_dwordx4 v[20:23], v[66:67], off
	s_nop 1
	v_readlane_b32 s4, v253, 28
	v_readlane_b32 s5, v253, 29
	s_nop 3
	v_lshl_add_u64 v[66:67], s[4:5], 0, v[144:145]
	s_nop 1
	global_load_dwordx4 v[24:27], v[66:67], off offset:16
	global_load_dwordx4 v[28:31], v[66:67], off
	s_nop 1
	v_readlane_b32 s4, v253, 30
	v_readlane_b32 s5, v253, 31
	s_nop 3
	v_lshl_add_u64 v[66:67], s[4:5], 0, v[144:145]
	s_nop 1
	global_load_dwordx4 v[32:35], v[66:67], off offset:16
	global_load_dwordx4 v[36:39], v[66:67], off
	s_nop 1
	v_readlane_b32 s4, v253, 34
	v_readlane_b32 s5, v253, 35
	s_nop 3
	v_lshl_add_u64 v[66:67], s[4:5], 0, v[144:145]
	s_nop 1
	global_load_dwordx4 v[40:43], v[66:67], off offset:16
	global_load_dwordx4 v[44:47], v[66:67], off
	s_nop 1
	v_readlane_b32 s4, v253, 20
	v_readlane_b32 s5, v253, 21
	s_nop 3
	v_lshl_add_u64 v[66:67], s[4:5], 0, v[144:145]
	s_nop 1
	global_load_dwordx4 v[48:51], v[66:67], off offset:16
	global_load_dwordx4 v[52:55], v[66:67], off
	s_nop 1
	v_readlane_b32 s4, v253, 22
	v_readlane_b32 s5, v253, 23
	s_nop 3
	v_lshl_add_u64 v[66:67], s[4:5], 0, v[144:145]
	s_nop 1
	global_load_dwordx4 v[56:59], v[66:67], off offset:16
	global_load_dwordx4 v[60:63], v[66:67], off
	s_nop 1
	v_readlane_b32 s4, v251, 1
	v_readlane_b32 s5, v251, 2
	s_mov_b32 s8, 0xb000
	s_sub_u32 s4, s4, 0x5800
	s_subb_u32 s5, s5, 0
	v_mad_u64_u32 v[64:65], s[6:7], v98, s8, v[146:147]
	s_nop 1
	v_lshl_add_u64 v[64:65], s[4:5], 0, v[64:65]
	s_movk_i32 s4, 0x1600
	s_mov_b32 s5, 0
	v_lshl_add_u64 v[66:67], v[64:65], 0, s[4:5]
	global_load_dwordx4 v[72:75], v[64:65], off
	v_lshl_add_u64 v[68:69], v[66:67], 0, s[4:5]
	global_load_dwordx4 v[88:91], v[66:67], off
	v_lshl_add_u64 v[70:71], v[68:69], 0, s[4:5]
	global_load_dwordx4 v[76:79], v[68:69], off
	v_lshl_add_u64 v[148:149], v[70:71], 0, s[4:5]
	global_load_dwordx4 v[92:95], v[70:71], off
	v_lshl_add_u64 v[150:151], v[148:149], 0, s[4:5]
	global_load_dwordx4 v[80:83], v[148:149], off
	v_lshl_add_u64 v[152:153], v[150:151], 0, s[4:5]
	global_load_dwordx4 v[100:103], v[150:151], off
	v_lshl_add_u64 v[154:155], v[152:153], 0, s[4:5]
	global_load_dwordx4 v[84:87], v[152:153], off
	global_load_dwordx4 v[104:107], v[154:155], off
	v_readlane_b32 s6, v250, 38
	v_readlane_b32 s7, v250, 39
	s_mov_b32 s8, 0x58000
	v_mad_u64_u32 v[156:157], vcc, v98, s8, v[146:147]
	s_nop 1
	v_lshl_add_u64 v[156:157], s[6:7], 0, v[156:157]
	s_nop 1
	v_lshl_add_u64 v[116:117], v[156:157], 0, s[4:5]
	v_cmp_eq_u32_e32 vcc, 0, v99
	s_mov_b32 s6, 0xbfb8aa3b
	s_mov_b32 s7, 0xbfb8aa3b
	s_mov_b32 s8, 1.0
	s_mov_b32 s9, 1.0
	s_waitcnt vmcnt(0)
	v_cndmask_b32_e32 v72, v72, v197, vcc
	v_cndmask_b32_e32 v73, v73, v197, vcc
	v_cndmask_b32_e32 v74, v74, v197, vcc
	v_cndmask_b32_e32 v75, v75, v197, vcc
	v_cndmask_b32_e32 v76, v76, v197, vcc
	v_cndmask_b32_e32 v77, v77, v197, vcc
	v_cndmask_b32_e32 v78, v78, v197, vcc
	v_cndmask_b32_e32 v79, v79, v197, vcc
	v_cndmask_b32_e32 v88, v88, v197, vcc
	v_cndmask_b32_e32 v89, v89, v197, vcc
	v_cndmask_b32_e32 v90, v90, v197, vcc
	v_cndmask_b32_e32 v91, v91, v197, vcc
	v_cndmask_b32_e32 v92, v92, v197, vcc
	v_cndmask_b32_e32 v93, v93, v197, vcc
	v_cndmask_b32_e32 v94, v94, v197, vcc
	v_cndmask_b32_e32 v95, v95, v197, vcc
	v_mov_b64_e32 v[64:65], v[156:157]
	v_mov_b64_e32 v[66:67], v[116:117]
	v_cvt_f32_f16_e32 v116, v72
	v_cvt_f32_f16_sdwa v117, v72 dst_sel:DWORD dst_unused:UNUSED_PAD src0_sel:WORD_1
	v_cvt_f32_f16_e32 v118, v76
	v_cvt_f32_f16_sdwa v119, v76 dst_sel:DWORD dst_unused:UNUSED_PAD src0_sel:WORD_1
	v_cvt_f32_f16_e32 v120, v80
	v_cvt_f32_f16_sdwa v121, v80 dst_sel:DWORD dst_unused:UNUSED_PAD src0_sel:WORD_1
	v_cvt_f32_f16_e32 v122, v84
	v_cvt_f32_f16_sdwa v123, v84 dst_sel:DWORD dst_unused:UNUSED_PAD src0_sel:WORD_1
	v_cvt_f32_f16_e32 v124, v88
	v_cvt_f32_f16_sdwa v125, v88 dst_sel:DWORD dst_unused:UNUSED_PAD src0_sel:WORD_1
	v_cvt_f32_f16_e32 v126, v92
	v_cvt_f32_f16_sdwa v127, v92 dst_sel:DWORD dst_unused:UNUSED_PAD src0_sel:WORD_1
	v_cvt_f32_f16_e32 v128, v100
	v_cvt_f32_f16_sdwa v129, v100 dst_sel:DWORD dst_unused:UNUSED_PAD src0_sel:WORD_1
	v_cvt_f32_f16_e32 v130, v104
	v_cvt_f32_f16_sdwa v131, v104 dst_sel:DWORD dst_unused:UNUSED_PAD src0_sel:WORD_1
	v_pk_fma_f32 v[132:133], v[36:37], v[120:121], v[52:53]
; __device__ __forceinline__ u32x4 pack8(f32x4 a, f32x4 b) { u32x4 w; w.x = pk2(a[0], a[1]); w.y = pk2(a[2], a[3]); w.z = pk2(b[0], b[1]); w.w = pk2(b[2], b[3]); return w; }
; __device__ __forceinline__ float sigmoidf_(float x) { return __builtin_amdgcn_rcpf(1.0f + __expf(-x)); }
; __device__ __forceinline__ void conv_phase(const Params& p, int layer) {
;     ...
;                 for (int e = 0; e < 8; ++e) {
;                     const float G = wg[0][e] * g2[e] + wg[1][e] * g1[e] + wg[2][e] * g0[e] + bg[e];
;                     const float V = wv[0][e] * v2[e] + wv[1][e] * v1[e] + wv[2][e] * v0[e] + bv[e];
;                     o[e] = G * sigmoidf_(G) * V;
;                     g2[e] = g1[e]; g1[e] = g0[e]; v2[e] = v1[e]; v1[e] = v0[e];
;                 }
;                 *(u32x4*)(act + (size_t)(r0 + i0 + i) * DFF + f) = pack8((f32x4){o[0], o[1], o[2], o[3]}, (f32x4){o[4], o[5], o[6], o[7]});
	v_pk_fma_f32 v[134:135], v[44:45], v[128:129], v[60:61]
	v_pk_fma_f32 v[136:137], v[36:37], v[122:123], v[52:53]
	v_pk_fma_f32 v[138:139], v[44:45], v[130:131], v[60:61]
	v_pk_fma_f32 v[132:133], v[20:21], v[118:119], v[132:133]
	v_pk_fma_f32 v[134:135], v[28:29], v[126:127], v[134:135]
	v_pk_fma_f32 v[136:137], v[20:21], v[120:121], v[136:137]
	v_pk_fma_f32 v[138:139], v[28:29], v[128:129], v[138:139]
	v_pk_fma_f32 v[132:133], v[4:5], v[116:117], v[132:133]
	v_pk_fma_f32 v[134:135], v[12:13], v[124:125], v[134:135]
	v_pk_fma_f32 v[136:137], v[4:5], v[118:119], v[136:137]
	v_pk_fma_f32 v[138:139], v[12:13], v[126:127], v[138:139]
	s_nop 0
	v_pk_mul_f32 v[140:141], v[132:133], s[6:7]
	v_pk_mul_f32 v[142:143], v[136:137], s[6:7]
	s_nop 0
	v_exp_f32_e32 v140, v140
	v_exp_f32_e32 v141, v141
	v_exp_f32_e32 v142, v142
	v_exp_f32_e32 v143, v143
	s_nop 0
	v_pk_add_f32 v[140:141], v[140:141], s[8:9]
	v_pk_add_f32 v[142:143], v[142:143], s[8:9]
	s_nop 0
	v_rcp_f32_e32 v140, v140
	v_rcp_f32_e32 v141, v141
	v_rcp_f32_e32 v142, v142
	v_rcp_f32_e32 v143, v143
	v_pk_mul_f32 v[132:133], v[132:133], v[134:135]
	v_pk_mul_f32 v[136:137], v[136:137], v[138:139]
	s_nop 0
	v_pk_mul_f32 v[132:133], v[132:133], v[140:141]
	v_pk_mul_f32 v[136:137], v[136:137], v[142:143]
	s_nop 0
	v_cvt_pk_f16_f32 v108, v132, v133
	v_cvt_pk_f16_f32 v112, v136, v137
	v_cvt_f32_f16_e32 v116, v73
	v_cvt_f32_f16_sdwa v117, v73 dst_sel:DWORD dst_unused:UNUSED_PAD src0_sel:WORD_1
	v_cvt_f32_f16_e32 v118, v77
	v_cvt_f32_f16_sdwa v119, v77 dst_sel:DWORD dst_unused:UNUSED_PAD src0_sel:WORD_1
	v_cvt_f32_f16_e32 v120, v81
	v_cvt_f32_f16_sdwa v121, v81 dst_sel:DWORD dst_unused:UNUSED_PAD src0_sel:WORD_1
	v_cvt_f32_f16_e32 v122, v85
	v_cvt_f32_f16_sdwa v123, v85 dst_sel:DWORD dst_unused:UNUSED_PAD src0_sel:WORD_1
	v_cvt_f32_f16_e32 v124, v89
	v_cvt_f32_f16_sdwa v125, v89 dst_sel:DWORD dst_unused:UNUSED_PAD src0_sel:WORD_1
	v_cvt_f32_f16_e32 v126, v93
	v_cvt_f32_f16_sdwa v127, v93 dst_sel:DWORD dst_unused:UNUSED_PAD src0_sel:WORD_1
	v_cvt_f32_f16_e32 v128, v101
	v_cvt_f32_f16_sdwa v129, v101 dst_sel:DWORD dst_unused:UNUSED_PAD src0_sel:WORD_1
	v_cvt_f32_f16_e32 v130, v105
	v_cvt_f32_f16_sdwa v131, v105 dst_sel:DWORD dst_unused:UNUSED_PAD src0_sel:WORD_1
	v_pk_fma_f32 v[132:133], v[38:39], v[120:121], v[54:55]
	v_pk_fma_f32 v[134:135], v[46:47], v[128:129], v[62:63]
	v_pk_fma_f32 v[136:137], v[38:39], v[122:123], v[54:55]
	v_pk_fma_f32 v[138:139], v[46:47], v[130:131], v[62:63]
	v_pk_fma_f32 v[132:133], v[22:23], v[118:119], v[132:133]
	v_pk_fma_f32 v[134:135], v[30:31], v[126:127], v[134:135]
	v_pk_fma_f32 v[136:137], v[22:23], v[120:121], v[136:137]
	v_pk_fma_f32 v[138:139], v[30:31], v[128:129], v[138:139]
	v_pk_fma_f32 v[132:133], v[6:7], v[116:117], v[132:133]
	v_pk_fma_f32 v[134:135], v[14:15], v[124:125], v[134:135]
	v_pk_fma_f32 v[136:137], v[6:7], v[118:119], v[136:137]
	v_pk_fma_f32 v[138:139], v[14:15], v[126:127], v[138:139]
	s_nop 0
	v_pk_mul_f32 v[140:141], v[132:133], s[6:7]
	v_pk_mul_f32 v[142:143], v[136:137], s[6:7]
	s_nop 0
	v_exp_f32_e32 v140, v140
	v_exp_f32_e32 v141, v141
	v_exp_f32_e32 v142, v142
	v_exp_f32_e32 v143, v143
	s_nop 0
	v_pk_add_f32 v[140:141], v[140:141], s[8:9]
	v_pk_add_f32 v[142:143], v[142:143], s[8:9]
	s_nop 0
	v_rcp_f32_e32 v140, v140
	v_rcp_f32_e32 v141, v141
	v_rcp_f32_e32 v142, v142
	v_rcp_f32_e32 v143, v143
	v_pk_mul_f32 v[132:133], v[132:133], v[134:135]
	v_pk_mul_f32 v[136:137], v[136:137], v[138:139]
	s_nop 0
	v_pk_mul_f32 v[132:133], v[132:133], v[140:141]
	v_pk_mul_f32 v[136:137], v[136:137], v[142:143]
	s_nop 0
	v_cvt_pk_f16_f32 v109, v132, v133
	v_cvt_pk_f16_f32 v113, v136, v137
	v_cvt_f32_f16_e32 v116, v74
	v_cvt_f32_f16_sdwa v117, v74 dst_sel:DWORD dst_unused:UNUSED_PAD src0_sel:WORD_1
	v_cvt_f32_f16_e32 v118, v78
	v_cvt_f32_f16_sdwa v119, v78 dst_sel:DWORD dst_unused:UNUSED_PAD src0_sel:WORD_1
	v_cvt_f32_f16_e32 v120, v82
	v_cvt_f32_f16_sdwa v121, v82 dst_sel:DWORD dst_unused:UNUSED_PAD src0_sel:WORD_1
	v_cvt_f32_f16_e32 v122, v86
	v_cvt_f32_f16_sdwa v123, v86 dst_sel:DWORD dst_unused:UNUSED_PAD src0_sel:WORD_1
	v_cvt_f32_f16_e32 v124, v90
	v_cvt_f32_f16_sdwa v125, v90 dst_sel:DWORD dst_unused:UNUSED_PAD src0_sel:WORD_1
	v_cvt_f32_f16_e32 v126, v94
	v_cvt_f32_f16_sdwa v127, v94 dst_sel:DWORD dst_unused:UNUSED_PAD src0_sel:WORD_1
; __device__ __forceinline__ void conv_phase(const Params& p, int layer) {
;     ...
;     for (size_t task = gtid; task < ntask; task += nth) {
;         const int cgp = (int)(task % 352), rc = (int)(task / 352), f = cgp * 8, r0 = rc * 16;
;         float wg[3][8], wv[3][8], bg[8], bv[8];
; #pragma unroll
;         for (int jj = 0; jj < 3; ++jj)
; #pragma unroll
;             for (int hlf = 0; hlf < 2; ++hlf) {
;                 const f32x4 a = *(const f32x4*)(cw + jj * 5632 + f + hlf * 4), c = *(const f32x4*)(cw + jj * 5632 + DFF + f + hlf * 4);
; #pragma unroll
;                 for (int e = 0; e < 4; ++e) { wg[jj][hlf * 4 + e] = a[e]; wv[jj][hlf * 4 + e] = c[e]; }
;             }
; #pragma unroll
;         for (int hlf = 0; hlf < 2; ++hlf) {
;             const f32x4 a = *(const f32x4*)(cb + f + hlf * 4), c = *(const f32x4*)(cb + DFF + f + hlf * 4);
; #pragma unroll
;             for (int e = 0; e < 4; ++e) { bg[hlf * 4 + e] = a[e]; bv[hlf * 4 + e] = c[e]; }
;         }
;         float g2[8], g1[8], v2[8], v1[8];
; #pragma unroll
;         for (int e = 0; e < 8; ++e) { g2[e] = 0.f; g1[e] = 0.f; v2[e] = 0.f; v1[e] = 0.f; }
;         if ((r0 & 2047) != 0) {
;             unpack8(*(const u32x4*)(u + (size_t)(r0 - 2) * 5632 + f), g2); unpack8(*(const u32x4*)(u + (size_t)(r0 - 1) * 5632 + f), g1);
;             unpack8(*(const u32x4*)(u + (size_t)(r0 - 2) * 5632 + DFF + f), v2); unpack8(*(const u32x4*)(u + (size_t)(r0 - 1) * 5632 + DFF + f), v1);
;         }
; #pragma unroll 1
;         for (int i0 = 0; i0 < 16; i0 += 4) {
;             u32x4 lg[4], lv[4];
; #pragma unroll
;             for (int i = 0; i < 4; ++i) { const size_t ro = (size_t)(r0 + i0 + i) * 5632; lg[i] = *(const u32x4*)(u + ro + f); lv[i] = *(const u32x4*)(u + ro + DFF + f); }
; #pragma unroll
;             for (int i = 0; i < 4; ++i) {
;                 float g0[8], v0[8], o[8];
;                 unpack8(lg[i], g0); unpack8(lv[i], v0);
; #pragma unroll
;                 for (int e = 0; e < 8; ++e) {
;                     const float G = wg[0][e] * g2[e] + wg[1][e] * g1[e] + wg[2][e] * g0[e] + bg[e];
;                     const float V = wv[0][e] * v2[e] + wv[1][e] * v1[e] + wv[2][e] * v0[e] + bv[e];
;                     o[e] = G * sigmoidf_(G) * V;
;                     g2[e] = g1[e]; g1[e] = g0[e]; v2[e] = v1[e]; v1[e] = v0[e];
;                 }
	v_cvt_f32_f16_e32 v128, v102
	v_cvt_f32_f16_sdwa v129, v102 dst_sel:DWORD dst_unused:UNUSED_PAD src0_sel:WORD_1
	v_cvt_f32_f16_e32 v130, v106
	v_cvt_f32_f16_sdwa v131, v106 dst_sel:DWORD dst_unused:UNUSED_PAD src0_sel:WORD_1
	v_pk_fma_f32 v[132:133], v[32:33], v[120:121], v[48:49]
	v_pk_fma_f32 v[134:135], v[40:41], v[128:129], v[56:57]
	v_pk_fma_f32 v[136:137], v[32:33], v[122:123], v[48:49]
	v_pk_fma_f32 v[138:139], v[40:41], v[130:131], v[56:57]
	v_pk_fma_f32 v[132:133], v[16:17], v[118:119], v[132:133]
	v_pk_fma_f32 v[134:135], v[24:25], v[126:127], v[134:135]
	v_pk_fma_f32 v[136:137], v[16:17], v[120:121], v[136:137]
	v_pk_fma_f32 v[138:139], v[24:25], v[128:129], v[138:139]
	v_pk_fma_f32 v[132:133], v[0:1], v[116:117], v[132:133]
	v_pk_fma_f32 v[134:135], v[8:9], v[124:125], v[134:135]
	v_pk_fma_f32 v[136:137], v[0:1], v[118:119], v[136:137]
	v_pk_fma_f32 v[138:139], v[8:9], v[126:127], v[138:139]
	s_nop 0
	v_pk_mul_f32 v[140:141], v[132:133], s[6:7]
	v_pk_mul_f32 v[142:143], v[136:137], s[6:7]
	s_nop 0
	v_exp_f32_e32 v140, v140
	v_exp_f32_e32 v141, v141
	v_exp_f32_e32 v142, v142
	v_exp_f32_e32 v143, v143
	s_nop 0
	v_pk_add_f32 v[140:141], v[140:141], s[8:9]
	v_pk_add_f32 v[142:143], v[142:143], s[8:9]
	s_nop 0
	v_rcp_f32_e32 v140, v140
	v_rcp_f32_e32 v141, v141
	v_rcp_f32_e32 v142, v142
	v_rcp_f32_e32 v143, v143
	v_pk_mul_f32 v[132:133], v[132:133], v[134:135]
	v_pk_mul_f32 v[136:137], v[136:137], v[138:139]
	s_nop 0
	v_pk_mul_f32 v[132:133], v[132:133], v[140:141]
	v_pk_mul_f32 v[136:137], v[136:137], v[142:143]
	s_nop 0
	v_cvt_pk_f16_f32 v110, v132, v133
	v_cvt_pk_f16_f32 v114, v136, v137
	v_cvt_f32_f16_e32 v116, v75
	v_cvt_f32_f16_sdwa v117, v75 dst_sel:DWORD dst_unused:UNUSED_PAD src0_sel:WORD_1
	v_cvt_f32_f16_e32 v118, v79
	v_cvt_f32_f16_sdwa v119, v79 dst_sel:DWORD dst_unused:UNUSED_PAD src0_sel:WORD_1
	v_cvt_f32_f16_e32 v120, v83
	v_cvt_f32_f16_sdwa v121, v83 dst_sel:DWORD dst_unused:UNUSED_PAD src0_sel:WORD_1
	v_cvt_f32_f16_e32 v122, v87
	v_cvt_f32_f16_sdwa v123, v87 dst_sel:DWORD dst_unused:UNUSED_PAD src0_sel:WORD_1
	v_cvt_f32_f16_e32 v124, v91
	v_cvt_f32_f16_sdwa v125, v91 dst_sel:DWORD dst_unused:UNUSED_PAD src0_sel:WORD_1
	v_cvt_f32_f16_e32 v126, v95
	v_cvt_f32_f16_sdwa v127, v95 dst_sel:DWORD dst_unused:UNUSED_PAD src0_sel:WORD_1
	v_cvt_f32_f16_e32 v128, v103
	v_cvt_f32_f16_sdwa v129, v103 dst_sel:DWORD dst_unused:UNUSED_PAD src0_sel:WORD_1
	v_cvt_f32_f16_e32 v130, v107
	v_cvt_f32_f16_sdwa v131, v107 dst_sel:DWORD dst_unused:UNUSED_PAD src0_sel:WORD_1
	v_pk_fma_f32 v[132:133], v[34:35], v[120:121], v[50:51]
	v_pk_fma_f32 v[134:135], v[42:43], v[128:129], v[58:59]
	v_pk_fma_f32 v[136:137], v[34:35], v[122:123], v[50:51]
	v_pk_fma_f32 v[138:139], v[42:43], v[130:131], v[58:59]
	v_pk_fma_f32 v[132:133], v[18:19], v[118:119], v[132:133]
	v_pk_fma_f32 v[134:135], v[26:27], v[126:127], v[134:135]
	v_pk_fma_f32 v[136:137], v[18:19], v[120:121], v[136:137]
	v_pk_fma_f32 v[138:139], v[26:27], v[128:129], v[138:139]
	v_pk_fma_f32 v[132:133], v[2:3], v[116:117], v[132:133]
	v_pk_fma_f32 v[134:135], v[10:11], v[124:125], v[134:135]
	v_pk_fma_f32 v[136:137], v[2:3], v[118:119], v[136:137]
	v_pk_fma_f32 v[138:139], v[10:11], v[126:127], v[138:139]
	s_nop 0
	v_pk_mul_f32 v[140:141], v[132:133], s[6:7]
	v_pk_mul_f32 v[142:143], v[136:137], s[6:7]
	s_nop 0
	v_exp_f32_e32 v140, v140
	v_exp_f32_e32 v141, v141
	v_exp_f32_e32 v142, v142
	v_exp_f32_e32 v143, v143
	s_nop 0
	v_pk_add_f32 v[140:141], v[140:141], s[8:9]
	v_pk_add_f32 v[142:143], v[142:143], s[8:9]
	s_nop 0
	v_rcp_f32_e32 v140, v140
	v_rcp_f32_e32 v141, v141
	v_rcp_f32_e32 v142, v142
	v_rcp_f32_e32 v143, v143
	v_pk_mul_f32 v[132:133], v[132:133], v[134:135]
	v_pk_mul_f32 v[136:137], v[136:137], v[138:139]
	s_nop 0
	v_pk_mul_f32 v[132:133], v[132:133], v[140:141]
	v_pk_mul_f32 v[136:137], v[136:137], v[142:143]
	s_nop 0
	v_cvt_pk_f16_f32 v111, v132, v133
	v_cvt_pk_f16_f32 v115, v136, v137
	s_nop 0
	global_store_dwordx4 v[64:65], v[108:111], off
	global_store_dwordx4 v[66:67], v[112:115], off
	v_readlane_b32 s4, v250, 42
	v_readlane_b32 s5, v250, 43
	s_nop 1
	v_lshl_add_u64 v[96:97], v[96:97], 0, s[4:5]
	s_mov_b64 s[4:5], 0x2bfff
	v_cmp_lt_u64_e32 vcc, s[4:5], v[96:97]
	s_or_b64 s[2:3], vcc, s[2:3]
	s_andn2_b64 exec, exec, s[2:3]
	s_cbranch_execnz .LBB0_476

; __device__ __forceinline__ void prep_phase(const Params& p, unsigned char* smem) {
;     ...
;     for (int id = 0; id < 42; ++id) {
;         const TJob J = get_job(p, id);
;         const int tk = J.ldd >> 6, tn = (J.N + 63) >> 6, ntile = tk * tn;
;         for (int tix = (int)((blockIdx.x + gridDim.x - (unsigned)(id * 37) % gridDim.x) % gridDim.x); tix < ntile; tix += gridDim.x) {
;             const int k0 = (tix % tk) * 64, n0 = (tix / tk) * 64;
.LBB0_596:
	s_sub_u32 s10, s20, 26
	s_cmp_lt_u32 s10, 8
	s_cselect_b32 s10, -1, 0
	s_bitcmp0_b32 s20, 0
	s_cselect_b32 s10, s10, 0
	v_mov_b32_e32 v30, s10
	s_add_i32 s10, s21, 63
	s_lshr_b32 s24, s22, 6
	s_lshr_b32 s10, s10, 6
	s_mul_i32 s25, s24, s10
	s_mul_i32 s10, s20, 37
	v_readlane_b32 s12, v251, 16
	s_mul_hi_u32 s11, s10, s12
	s_mul_i32 s11, s11, s46
	s_sub_i32 s10, s10, s11
	s_sub_i32 s11, s10, s46
	s_cmp_ge_u32 s10, s46
	s_cselect_b32 s10, s11, s10
	s_sub_i32 s11, s10, s46
	s_cmp_ge_u32 s10, s46
	s_cselect_b32 s10, s11, s10
	v_readlane_b32 s11, v250, 50
	s_sub_i32 s10, s11, s10
	s_mul_hi_u32 s11, s10, s12
	s_mul_i32 s11, s11, s46
	s_sub_i32 s10, s10, s11
	s_sub_i32 s11, s10, s46
	s_cmp_ge_u32 s10, s46
	s_cselect_b32 s10, s11, s10
	s_sub_i32 s11, s10, s46
	s_cmp_ge_u32 s10, s46
	s_cselect_b32 s26, s11, s10
	s_cmp_ge_i32 s26, s25
	s_cbranch_scc1 .LBB0_535
	v_cvt_f32_u32_e32 v4, s24
	v_lshlrev_b32_e32 v196, 1, v0
	v_lshl_add_u64 v[2:3], s[0:1], 0, v[196:197]
	s_sub_i32 s0, 0, s24
	v_rcp_iflag_f32_e32 v4, v4
	s_xor_b64 s[10:11], s[16:17], -1
	s_add_i32 s27, s23, s27
	v_subrev_u32_e32 v15, s23, v1
	v_mul_f32_e32 v4, 0x4f7ffffe, v4
	v_cvt_u32_f32_e32 v4, v4
	s_lshl_b32 s30, s26, 6
	s_xor_b64 s[12:13], s[4:5], -1
	v_readfirstlane_b32 s1, v4
	s_mul_i32 s0, s0, s1
	s_mul_hi_u32 s0, s1, s0
	s_add_i32 s28, s1, s0
	s_lshl_b32 s0, s24, 6
	s_sub_i32 s29, 0, s0
	s_branch .LBB0_599

; __device__ __forceinline__ void prep_phase(const Params& p, unsigned char* smem) {
;     ...
; #pragma unroll
;             for (int i = 0; i < 8; ++i) {
;                 const int n = i * 8 + (tid >> 6), k = tid & 63, nn = n0 + n;
;                 if (nn < J.N) J.dst[(size_t)nn * J.ldd + k0 + k] = (h16)tile[k * 65 + n];
;             }
.Ltr_join:
	s_waitcnt lgkmcnt(0)
	s_barrier
	s_and_saveexec_b64 s[0:1], vcc
	s_cbranch_execz .LBB0_661
	ds_read_b32 v19, v13
	v_cmp_le_u32_e32 vcc, 0xb00, v16
	v_subrev_u32_e32 v22, 0xb00, v16
	s_nop 0
	v_cndmask_b32_e32 v22, v16, v22, vcc
	v_cndmask_b32_e64 v23, 0, 1, vcc
	v_and_b32_e32 v24, 0x7f, v22
	v_lshrrev_b32_e32 v22, 7, v22
	v_lshl_or_b32 v22, v22, 8, v24
	v_lshl_or_b32 v22, v23, 7, v22
	v_bfi_b32 v16, v30, v22, v16
	v_ashrrev_i32_e32 v20, 31, v16
	v_mad_u64_u32 v[16:17], s[4:5], v16, s22, 0
	v_mov_b32_e32 v18, v17
	s_waitcnt lgkmcnt(0)
	v_cvt_f16_f32_e32 v21, v19
	v_mad_u64_u32 v[18:19], s[4:5], v20, s22, v[18:19]
	v_mov_b32_e32 v17, v18
	v_lshl_add_u64 v[16:17], v[16:17], 1, v[4:5]
	global_store_short v[16:17], v21, off
.LBB0_661:
	s_or_b64 exec, exec, s[0:1]
	v_add_u32_e32 v16, s31, v6
	v_cmp_gt_i32_e32 vcc, s21, v16
	s_and_saveexec_b64 s[0:1], vcc
	s_cbranch_execz .LBB0_663
	ds_read_b32 v19, v13 offset:32
	v_cmp_le_u32_e32 vcc, 0xb00, v16
	v_subrev_u32_e32 v22, 0xb00, v16
	s_nop 0
	v_cndmask_b32_e32 v22, v16, v22, vcc
	v_cndmask_b32_e64 v23, 0, 1, vcc
	v_and_b32_e32 v24, 0x7f, v22
	v_lshrrev_b32_e32 v22, 7, v22
	v_lshl_or_b32 v22, v22, 8, v24
	v_lshl_or_b32 v22, v23, 7, v22
	v_bfi_b32 v16, v30, v22, v16
	v_ashrrev_i32_e32 v20, 31, v16
	v_mad_u64_u32 v[16:17], s[4:5], v16, s22, 0
	v_mov_b32_e32 v18, v17
	s_waitcnt lgkmcnt(0)
	v_cvt_f16_f32_e32 v21, v19
	v_mad_u64_u32 v[18:19], s[4:5], v20, s22, v[18:19]
	v_mov_b32_e32 v17, v18
	v_lshl_add_u64 v[16:17], v[16:17], 1, v[4:5]
	global_store_short v[16:17], v21, off
.LBB0_663:
	s_or_b64 exec, exec, s[0:1]
	v_add_u32_e32 v16, s31, v7
	v_cmp_gt_i32_e32 vcc, s21, v16
	s_and_saveexec_b64 s[0:1], vcc
	s_cbranch_execz .LBB0_665
	ds_read_b32 v19, v13 offset:64
	v_cmp_le_u32_e32 vcc, 0xb00, v16
	v_subrev_u32_e32 v22, 0xb00, v16
	s_nop 0
	v_cndmask_b32_e32 v22, v16, v22, vcc
	v_cndmask_b32_e64 v23, 0, 1, vcc
	v_and_b32_e32 v24, 0x7f, v22
	v_lshrrev_b32_e32 v22, 7, v22
	v_lshl_or_b32 v22, v22, 8, v24
	v_lshl_or_b32 v22, v23, 7, v22
	v_bfi_b32 v16, v30, v22, v16
	v_ashrrev_i32_e32 v20, 31, v16
	v_mad_u64_u32 v[16:17], s[4:5], v16, s22, 0
	v_mov_b32_e32 v18, v17
	s_waitcnt lgkmcnt(0)
	v_cvt_f16_f32_e32 v21, v19
	v_mad_u64_u32 v[18:19], s[4:5], v20, s22, v[18:19]
	v_mov_b32_e32 v17, v18
	v_lshl_add_u64 v[16:17], v[16:17], 1, v[4:5]
	global_store_short v[16:17], v21, off
.LBB0_665:
	s_or_b64 exec, exec, s[0:1]
	v_add_u32_e32 v16, s31, v8
	v_cmp_gt_i32_e32 vcc, s21, v16
	s_and_saveexec_b64 s[0:1], vcc
	s_cbranch_execz .LBB0_667
	ds_read_b32 v19, v13 offset:96
	v_cmp_le_u32_e32 vcc, 0xb00, v16
	v_subrev_u32_e32 v22, 0xb00, v16
	s_nop 0
	v_cndmask_b32_e32 v22, v16, v22, vcc
	v_cndmask_b32_e64 v23, 0, 1, vcc
	v_and_b32_e32 v24, 0x7f, v22
	v_lshrrev_b32_e32 v22, 7, v22
	v_lshl_or_b32 v22, v22, 8, v24
	v_lshl_or_b32 v22, v23, 7, v22
	v_bfi_b32 v16, v30, v22, v16
	v_ashrrev_i32_e32 v20, 31, v16
	v_mad_u64_u32 v[16:17], s[4:5], v16, s22, 0
	v_mov_b32_e32 v18, v17
	s_waitcnt lgkmcnt(0)
	v_cvt_f16_f32_e32 v21, v19
	v_mad_u64_u32 v[18:19], s[4:5], v20, s22, v[18:19]
	v_mov_b32_e32 v17, v18
	v_lshl_add_u64 v[16:17], v[16:17], 1, v[4:5]
	global_store_short v[16:17], v21, off
.LBB0_667:
	s_or_b64 exec, exec, s[0:1]
	v_add_u32_e32 v16, s31, v9
	v_cmp_gt_i32_e32 vcc, s21, v16
	s_and_saveexec_b64 s[0:1], vcc
	s_cbranch_execz .LBB0_669
	ds_read_b32 v19, v13 offset:128
	v_cmp_le_u32_e32 vcc, 0xb00, v16
	v_subrev_u32_e32 v22, 0xb00, v16
	s_nop 0
	v_cndmask_b32_e32 v22, v16, v22, vcc
	v_cndmask_b32_e64 v23, 0, 1, vcc
	v_and_b32_e32 v24, 0x7f, v22
	v_lshrrev_b32_e32 v22, 7, v22
	v_lshl_or_b32 v22, v22, 8, v24
	v_lshl_or_b32 v22, v23, 7, v22
	v_bfi_b32 v16, v30, v22, v16
	v_ashrrev_i32_e32 v20, 31, v16
	v_mad_u64_u32 v[16:17], s[4:5], v16, s22, 0
	v_mov_b32_e32 v18, v17
	s_waitcnt lgkmcnt(0)
	v_cvt_f16_f32_e32 v21, v19
	v_mad_u64_u32 v[18:19], s[4:5], v20, s22, v[18:19]
	v_mov_b32_e32 v17, v18
	v_lshl_add_u64 v[16:17], v[16:17], 1, v[4:5]
	global_store_short v[16:17], v21, off
.LBB0_669:
	s_or_b64 exec, exec, s[0:1]
	v_add_u32_e32 v16, s31, v10
	v_cmp_gt_i32_e32 vcc, s21, v16
	s_and_saveexec_b64 s[0:1], vcc
	s_cbranch_execz .LBB0_671
	ds_read_b32 v19, v13 offset:160
	v_cmp_le_u32_e32 vcc, 0xb00, v16
	v_subrev_u32_e32 v22, 0xb00, v16
	s_nop 0
	v_cndmask_b32_e32 v22, v16, v22, vcc
	v_cndmask_b32_e64 v23, 0, 1, vcc
	v_and_b32_e32 v24, 0x7f, v22
	v_lshrrev_b32_e32 v22, 7, v22
	v_lshl_or_b32 v22, v22, 8, v24
	v_lshl_or_b32 v22, v23, 7, v22
	v_bfi_b32 v16, v30, v22, v16
	v_ashrrev_i32_e32 v20, 31, v16
	v_mad_u64_u32 v[16:17], s[4:5], v16, s22, 0
	v_mov_b32_e32 v18, v17
	s_waitcnt lgkmcnt(0)
	v_cvt_f16_f32_e32 v21, v19
	v_mad_u64_u32 v[18:19], s[4:5], v20, s22, v[18:19]
	v_mov_b32_e32 v17, v18
	v_lshl_add_u64 v[16:17], v[16:17], 1, v[4:5]
	global_store_short v[16:17], v21, off
.LBB0_671:
	s_or_b64 exec, exec, s[0:1]
	v_add_u32_e32 v16, s31, v11
	v_cmp_gt_i32_e32 vcc, s21, v16
	s_and_saveexec_b64 s[0:1], vcc
	s_cbranch_execz .LBB0_673
	ds_read_b32 v19, v13 offset:192
	v_cmp_le_u32_e32 vcc, 0xb00, v16
	v_subrev_u32_e32 v22, 0xb00, v16
	s_nop 0
	v_cndmask_b32_e32 v22, v16, v22, vcc
	v_cndmask_b32_e64 v23, 0, 1, vcc
	v_and_b32_e32 v24, 0x7f, v22
	v_lshrrev_b32_e32 v22, 7, v22
	v_lshl_or_b32 v22, v22, 8, v24
	v_lshl_or_b32 v22, v23, 7, v22
	v_bfi_b32 v16, v30, v22, v16
	v_ashrrev_i32_e32 v20, 31, v16
	v_mad_u64_u32 v[16:17], s[4:5], v16, s22, 0
	v_mov_b32_e32 v18, v17
	s_waitcnt lgkmcnt(0)
	v_cvt_f16_f32_e32 v21, v19
	v_mad_u64_u32 v[18:19], s[4:5], v20, s22, v[18:19]
	v_mov_b32_e32 v17, v18
	v_lshl_add_u64 v[16:17], v[16:17], 1, v[4:5]
	global_store_short v[16:17], v21, off
.LBB0_673:
	s_or_b64 exec, exec, s[0:1]
	v_add_u32_e32 v16, s31, v12
	v_cmp_gt_i32_e32 vcc, s21, v16
	s_and_saveexec_b64 s[0:1], vcc
	s_cbranch_execz .LBB0_598
	ds_read_b32 v19, v13 offset:224
	v_cmp_le_u32_e32 vcc, 0xb00, v16
	v_subrev_u32_e32 v22, 0xb00, v16
	s_nop 0
	v_cndmask_b32_e32 v22, v16, v22, vcc
	v_cndmask_b32_e64 v23, 0, 1, vcc
	v_and_b32_e32 v24, 0x7f, v22
	v_lshrrev_b32_e32 v22, 7, v22
	v_lshl_or_b32 v22, v22, 8, v24
	v_lshl_or_b32 v22, v23, 7, v22
	v_bfi_b32 v16, v30, v22, v16
	v_ashrrev_i32_e32 v20, 31, v16
	v_mad_u64_u32 v[16:17], s[4:5], v16, s22, 0
	v_mov_b32_e32 v18, v17
	s_waitcnt lgkmcnt(0)
	v_cvt_f16_f32_e32 v21, v19
	v_mad_u64_u32 v[18:19], s[4:5], v20, s22, v[18:19]
	v_mov_b32_e32 v17, v18
	v_lshl_add_u64 v[4:5], v[16:17], 1, v[4:5]
	global_store_short v[4:5], v21, off
	s_branch .LBB0_598

;     __device__ __forceinline__ void operator()(const f32x4 (&acc)[2][2][4][2], const Unit& u, int wr, int wc, int fr, int fq) const {
;     ...
;                     } else if (mode == E_ST16) {
;                         *(u32x4*)((h16*)(ws + F_U16) + (size_t)rowl * 5632 + col) = pack8(v0, v1);
; __device__ __forceinline__ void conv_phase(const Params& p, int layer) {
;     ...
;         float wg[3][8], wv[3][8], bg[8], bv[8];
; #pragma unroll
;         for (int jj = 0; jj < 3; ++jj)
; #pragma unroll
;             for (int hlf = 0; hlf < 2; ++hlf) {
;                 const f32x4 a = *(const f32x4*)(cw + jj * 5632 + f + hlf * 4), c = *(const f32x4*)(cw + jj * 5632 + DFF + f + hlf * 4);
; #pragma unroll
;                 for (int e = 0; e < 4; ++e) { wg[jj][hlf * 4 + e] = a[e]; wv[jj][hlf * 4 + e] = c[e]; }
;             }
; #pragma unroll
;         for (int hlf = 0; hlf < 2; ++hlf) {
;             const f32x4 a = *(const f32x4*)(cb + f + hlf * 4), c = *(const f32x4*)(cb + DFF + f + hlf * 4);
; #pragma unroll
;             for (int e = 0; e < 4; ++e) { bg[hlf * 4 + e] = a[e]; bv[hlf * 4 + e] = c[e]; }
;         }
;         float g2[8], g1[8], v2[8], v1[8];
; #pragma unroll
;         for (int e = 0; e < 8; ++e) { g2[e] = 0.f; g1[e] = 0.f; v2[e] = 0.f; v1[e] = 0.f; }
;         if ((r0 & 2047) != 0) {
;             unpack8(*(const u32x4*)(u + (size_t)(r0 - 2) * 5632 + f), g2); unpack8(*(const u32x4*)(u + (size_t)(r0 - 1) * 5632 + f), g1);
;             unpack8(*(const u32x4*)(u + (size_t)(r0 - 2) * 5632 + DFF + f), v2); unpack8(*(const u32x4*)(u + (size_t)(r0 - 1) * 5632 + DFF + f), v1);
;         }
; #pragma unroll 1
;         for (int i0 = 0; i0 < 16; i0 += 4) {
;             u32x4 lg[4], lv[4];
; #pragma unroll
;             for (int i = 0; i < 4; ++i) { const size_t ro = (size_t)(r0 + i0 + i) * 5632; lg[i] = *(const u32x4*)(u + ro + f); lv[i] = *(const u32x4*)(u + ro + DFF + f); }
; #pragma unroll
;             for (int i = 0; i < 4; ++i) {
;                 float g0[8], v0[8], o[8];
;                 unpack8(lg[i], g0); unpack8(lv[i], v0);
; #pragma unroll
;                 for (int e = 0; e < 8; ++e) {
;                     const float G = wg[0][e] * g2[e] + wg[1][e] * g1[e] + wg[2][e] * g0[e] + bg[e];
;                     const float V = wv[0][e] * v2[e] + wv[1][e] * v1[e] + wv[2][e] * v0[e] + bv[e];
;                     o[e] = G * sigmoidf_(G) * V;
.Lst16_fast:
	v_readlane_b32 s0, v253, 32
	v_readlane_b32 s1, v253, 33
	v_readlane_b32 s86, v253, 20
	v_readlane_b32 s87, v253, 21
	s_lshl_b32 s27, s84, 7
	s_add_i32 s27, s27, s65
	v_add_u32_e32 v216, s27, v202
	v_lshlrev_b32_e32 v216, 2, v216
	v_add_u32_e32 v217, 0x2c00, v216
	v_add_u32_e32 v218, 0x5800, v216
	v_add_u32_e32 v219, 0x8400, v216
	v_add_u32_e32 v220, 0xb000, v216
	v_add_u32_e32 v221, 0xdc00, v216
	v_mov_b32_e32 v222, v216
	v_add_u32_e32 v223, 0x2c00, v216
	global_load_dwordx4 v[140:143], v222, s[86:87]
	global_load_dwordx4 v[156:159], v223, s[86:87]
	global_load_dwordx4 v[128:131], v216, s[0:1]
	global_load_dwordx4 v[144:147], v217, s[0:1]
	global_load_dwordx4 v[132:135], v218, s[0:1]
	global_load_dwordx4 v[148:151], v219, s[0:1]
	global_load_dwordx4 v[136:139], v220, s[0:1]
	global_load_dwordx4 v[152:155], v221, s[0:1]
	v_readlane_b32 s34, v251, 1
	v_readlane_b32 s35, v251, 2
	s_movk_i32 s33, 0x2c00
	s_lshl_b32 s27, s27, 1
	v_and_b32_e32 v160, 15, v240
	v_lshrrev_b32_e32 v161, 6, v240
	v_lshl_add_u32 v161, v161, 2, v160
	v_add_u32_e32 v162, -12, v161
	v_lshl_add_u32 v164, v202, 1, s27
	v_mov_b32_e32 v165, v197
	v_mad_u64_u32 v[166:167], s[86:87], v161, s33, v[164:165]
	v_mad_u64_u32 v[170:171], s[86:87], v162, s33, v[164:165]
	v_lshl_add_u64 v[166:167], s[34:35], 0, v[166:167]
	v_lshl_add_u64 v[170:171], s[34:35], 0, v[170:171]
	s_movk_i32 s36, 0x1600
	s_mov_b32 s37, 0
	s_mov_b32 s34, 0x14a00
	s_mov_b32 s35, 0
	v_cmp_gt_u32_e32 vcc, 2, v160
	v_cmp_lt_u32_e64 s[0:1], 13, v160
	s_mov_b64 s[38:39], exec
	s_and_b64 exec, s[38:39], vcc
	v_cvt_pk_f16_f32 v176, v124, v125
	v_cvt_pk_f16_f32 v177, v126, v127
	v_cvt_pk_f16_f32 v178, v120, v121
	v_cvt_pk_f16_f32 v179, v122, v123
	v_lshl_add_u64 v[168:169], v[166:167], 0, s[36:37]
	global_store_dwordx4 v[166:167], v[176:179], off
	v_cvt_pk_f16_f32 v180, v116, v117
	v_cvt_pk_f16_f32 v181, v118, v119
	v_cvt_pk_f16_f32 v182, v112, v113
	v_cvt_pk_f16_f32 v183, v114, v115
	v_lshl_add_u64 v[166:167], v[168:169], 0, s[34:35]
	global_store_dwordx4 v[168:169], v[180:183], off
	v_cvt_pk_f16_f32 v184, v60, v61
	v_cvt_pk_f16_f32 v185, v62, v63
	v_cvt_pk_f16_f32 v186, v56, v57
	v_cvt_pk_f16_f32 v187, v58, v59
	v_lshl_add_u64 v[168:169], v[166:167], 0, s[36:37]
	global_store_dwordx4 v[166:167], v[184:187], off
	v_cvt_pk_f16_f32 v188, v52, v53
	v_cvt_pk_f16_f32 v189, v54, v55
	v_cvt_pk_f16_f32 v190, v48, v49
	v_cvt_pk_f16_f32 v191, v50, v51
	global_store_dwordx4 v[168:169], v[188:191], off
	s_and_b64 exec, s[38:39], s[0:1]
	v_cvt_pk_f16_f32 v176, v76, v77
	v_cvt_pk_f16_f32 v177, v78, v79
	v_cvt_pk_f16_f32 v178, v72, v73
	v_cvt_pk_f16_f32 v179, v74, v75
	v_lshl_add_u64 v[172:173], v[170:171], 0, s[36:37]
	global_store_dwordx4 v[170:171], v[176:179], off
	v_cvt_pk_f16_f32 v180, v68, v69
	v_cvt_pk_f16_f32 v181, v70, v71
	v_cvt_pk_f16_f32 v182, v64, v65
	v_cvt_pk_f16_f32 v183, v66, v67
	v_lshl_add_u64 v[170:171], v[172:173], 0, s[34:35]
	global_store_dwordx4 v[172:173], v[180:183], off
	v_cvt_pk_f16_f32 v184, v12, v13
	v_cvt_pk_f16_f32 v185, v14, v15
	v_cvt_pk_f16_f32 v186, v8, v9
	v_cvt_pk_f16_f32 v187, v10, v11
	v_lshl_add_u64 v[172:173], v[170:171], 0, s[36:37]
	global_store_dwordx4 v[170:171], v[184:187], off
	v_cvt_pk_f16_f32 v188, v4, v5
	v_cvt_pk_f16_f32 v189, v6, v7
	v_cvt_pk_f16_f32 v190, v0, v1
	v_cvt_pk_f16_f32 v191, v2, v3
	global_store_dwordx4 v[172:173], v[188:191], off
	s_mov_b64 exec, s[38:39]
	v_readlane_b32 s0, v253, 32
	v_readlane_b32 s1, v253, 33
	v_readlane_b32 s86, v253, 20
	v_readlane_b32 s87, v253, 21
	s_mov_b32 s34, 0xbfb8aa3b
	s_mov_b32 s35, 0xbfb8aa3b
	s_mov_b32 s36, 1.0
	s_mov_b32 s37, 1.0
	s_nop 4
	global_load_dwordx4 v[172:175], v222, s[86:87] offset:16
	global_load_dwordx4 v[188:191], v223, s[86:87] offset:16
	global_load_dwordx4 v[160:163], v216, s[0:1] offset:16
	global_load_dwordx4 v[176:179], v217, s[0:1] offset:16
	global_load_dwordx4 v[164:167], v218, s[0:1] offset:16
	global_load_dwordx4 v[180:183], v219, s[0:1] offset:16
	global_load_dwordx4 v[168:171], v220, s[0:1] offset:16
	global_load_dwordx4 v[184:187], v221, s[0:1] offset:16
	s_waitcnt vmcnt(16)
	v_pk_fma_f32 v[192:193], v[76:77], v[136:137], v[140:141]
	v_pk_fma_f32 v[194:195], v[68:69], v[152:153], v[156:157]
	v_fmac_f32_dpp v192, v76, v132 row_shr:1 row_mask:0xf bank_mask:0xf
	v_fmac_f32_dpp v192, v92, v132 row_shl:15 row_mask:0xf bank_mask:0xf
	v_pk_fma_f32 v[218:219], v[78:79], v[138:139], v[142:143]
	v_fmac_f32_dpp v192, v76, v128 row_shr:2 row_mask:0xf bank_mask:0xf
	v_pk_fma_f32 v[220:221], v[70:71], v[154:155], v[158:159]
	v_fmac_f32_dpp v192, v92, v128 row_shl:14 row_mask:0xf bank_mask:0xf
	v_fmac_f32_dpp v218, v78, v134 row_shr:1 row_mask:0xf bank_mask:0xf
	v_fmac_f32_dpp v193, v77, v133 row_shr:1 row_mask:0xf bank_mask:0xf
	v_fmac_f32_dpp v218, v94, v134 row_shl:15 row_mask:0xf bank_mask:0xf
	v_fmac_f32_dpp v193, v93, v133 row_shl:15 row_mask:0xf bank_mask:0xf
	v_fmac_f32_dpp v218, v78, v130 row_shr:2 row_mask:0xf bank_mask:0xf
	v_fmac_f32_dpp v193, v77, v129 row_shr:2 row_mask:0xf bank_mask:0xf
	v_fmac_f32_dpp v218, v94, v130 row_shl:14 row_mask:0xf bank_mask:0xf
	v_fmac_f32_dpp v193, v93, v129 row_shl:14 row_mask:0xf bank_mask:0xf
	v_fmac_f32_dpp v219, v79, v135 row_shr:1 row_mask:0xf bank_mask:0xf
	v_fmac_f32_dpp v194, v68, v148 row_shr:1 row_mask:0xf bank_mask:0xf
	v_fmac_f32_dpp v219, v95, v135 row_shl:15 row_mask:0xf bank_mask:0xf
	v_fmac_f32_dpp v194, v84, v148 row_shl:15 row_mask:0xf bank_mask:0xf
	v_fmac_f32_dpp v219, v79, v131 row_shr:2 row_mask:0xf bank_mask:0xf
	v_fmac_f32_dpp v194, v68, v144 row_shr:2 row_mask:0xf bank_mask:0xf
	v_fmac_f32_dpp v219, v95, v131 row_shl:14 row_mask:0xf bank_mask:0xf
; __device__ __forceinline__ float sigmoidf_(float x) { return __builtin_amdgcn_rcpf(1.0f + __expf(-x)); }
; __device__ __forceinline__ void conv_phase(const Params& p, int layer) {
;     ...
;                 for (int e = 0; e < 8; ++e) {
;                     const float G = wg[0][e] * g2[e] + wg[1][e] * g1[e] + wg[2][e] * g0[e] + bg[e];
;                     const float V = wv[0][e] * v2[e] + wv[1][e] * v1[e] + wv[2][e] * v0[e] + bv[e];
;                     o[e] = G * sigmoidf_(G) * V;
	v_fmac_f32_dpp v194, v84, v144 row_shl:14 row_mask:0xf bank_mask:0xf
	v_fmac_f32_dpp v220, v70, v150 row_shr:1 row_mask:0xf bank_mask:0xf
	v_fmac_f32_dpp v195, v69, v149 row_shr:1 row_mask:0xf bank_mask:0xf
	v_fmac_f32_dpp v220, v86, v150 row_shl:15 row_mask:0xf bank_mask:0xf
	v_fmac_f32_dpp v195, v85, v149 row_shl:15 row_mask:0xf bank_mask:0xf
	v_fmac_f32_dpp v220, v70, v146 row_shr:2 row_mask:0xf bank_mask:0xf
	v_fmac_f32_dpp v195, v69, v145 row_shr:2 row_mask:0xf bank_mask:0xf
	v_fmac_f32_dpp v220, v86, v146 row_shl:14 row_mask:0xf bank_mask:0xf
	v_fmac_f32_dpp v195, v85, v145 row_shl:14 row_mask:0xf bank_mask:0xf
	v_fmac_f32_dpp v221, v71, v151 row_shr:1 row_mask:0xf bank_mask:0xf
	v_pk_mul_f32 v[216:217], v[192:193], s[34:35]
	v_fmac_f32_dpp v221, v87, v151 row_shl:15 row_mask:0xf bank_mask:0xf
	v_exp_f32_e32 v216, v216
	v_fmac_f32_dpp v221, v71, v147 row_shr:2 row_mask:0xf bank_mask:0xf
	v_exp_f32_e32 v217, v217
	v_fmac_f32_dpp v221, v87, v147 row_shl:14 row_mask:0xf bank_mask:0xf
	v_pk_add_f32 v[216:217], v[216:217], s[36:37]
	v_pk_mul_f32 v[222:223], v[218:219], s[34:35]
	v_rcp_f32_e32 v216, v216
	v_exp_f32_e32 v222, v222
	v_rcp_f32_e32 v217, v217
	v_exp_f32_e32 v223, v223
	v_pk_mul_f32 v[192:193], v[192:193], v[194:195]
	v_pk_add_f32 v[222:223], v[222:223], s[36:37]
	v_pk_mul_f32 v[76:77], v[192:193], v[216:217]
	v_rcp_f32_e32 v222, v222
	v_pk_fma_f32 v[192:193], v[92:93], v[136:137], v[140:141]
	v_rcp_f32_e32 v223, v223
	v_pk_fma_f32 v[194:195], v[84:85], v[152:153], v[156:157]
	v_pk_mul_f32 v[218:219], v[218:219], v[220:221]
	v_fmac_f32_dpp v192, v92, v132 row_shr:1 row_mask:0xf bank_mask:0xf
	v_pk_mul_f32 v[78:79], v[218:219], v[222:223]
	v_fmac_f32_dpp v192, v108, v132 row_shl:15 row_mask:0xf bank_mask:0xf
	v_pk_fma_f32 v[218:219], v[94:95], v[138:139], v[142:143]
	v_fmac_f32_dpp v192, v92, v128 row_shr:2 row_mask:0xf bank_mask:0xf
	v_pk_fma_f32 v[220:221], v[86:87], v[154:155], v[158:159]
	v_fmac_f32_dpp v192, v108, v128 row_shl:14 row_mask:0xf bank_mask:0xf
	v_fmac_f32_dpp v218, v94, v134 row_shr:1 row_mask:0xf bank_mask:0xf
	v_fmac_f32_dpp v193, v93, v133 row_shr:1 row_mask:0xf bank_mask:0xf
	v_fmac_f32_dpp v218, v110, v134 row_shl:15 row_mask:0xf bank_mask:0xf
	v_fmac_f32_dpp v193, v109, v133 row_shl:15 row_mask:0xf bank_mask:0xf
	v_fmac_f32_dpp v218, v94, v130 row_shr:2 row_mask:0xf bank_mask:0xf
	v_fmac_f32_dpp v193, v93, v129 row_shr:2 row_mask:0xf bank_mask:0xf
	v_fmac_f32_dpp v218, v110, v130 row_shl:14 row_mask:0xf bank_mask:0xf
	v_fmac_f32_dpp v193, v109, v129 row_shl:14 row_mask:0xf bank_mask:0xf
	v_fmac_f32_dpp v219, v95, v135 row_shr:1 row_mask:0xf bank_mask:0xf
	v_fmac_f32_dpp v194, v84, v148 row_shr:1 row_mask:0xf bank_mask:0xf
	v_fmac_f32_dpp v219, v111, v135 row_shl:15 row_mask:0xf bank_mask:0xf
	v_fmac_f32_dpp v194, v100, v148 row_shl:15 row_mask:0xf bank_mask:0xf
	v_fmac_f32_dpp v219, v95, v131 row_shr:2 row_mask:0xf bank_mask:0xf
	v_fmac_f32_dpp v194, v84, v144 row_shr:2 row_mask:0xf bank_mask:0xf
	v_fmac_f32_dpp v219, v111, v131 row_shl:14 row_mask:0xf bank_mask:0xf
	v_fmac_f32_dpp v194, v100, v144 row_shl:14 row_mask:0xf bank_mask:0xf
	v_fmac_f32_dpp v220, v86, v150 row_shr:1 row_mask:0xf bank_mask:0xf
	v_fmac_f32_dpp v195, v85, v149 row_shr:1 row_mask:0xf bank_mask:0xf
	v_fmac_f32_dpp v220, v102, v150 row_shl:15 row_mask:0xf bank_mask:0xf
	v_fmac_f32_dpp v195, v101, v149 row_shl:15 row_mask:0xf bank_mask:0xf
	v_fmac_f32_dpp v220, v86, v146 row_shr:2 row_mask:0xf bank_mask:0xf
	v_fmac_f32_dpp v195, v85, v145 row_shr:2 row_mask:0xf bank_mask:0xf
	v_fmac_f32_dpp v220, v102, v146 row_shl:14 row_mask:0xf bank_mask:0xf
	v_fmac_f32_dpp v195, v101, v145 row_shl:14 row_mask:0xf bank_mask:0xf
	v_fmac_f32_dpp v221, v87, v151 row_shr:1 row_mask:0xf bank_mask:0xf
	v_pk_mul_f32 v[216:217], v[192:193], s[34:35]
	v_fmac_f32_dpp v221, v103, v151 row_shl:15 row_mask:0xf bank_mask:0xf
	v_exp_f32_e32 v216, v216
	v_fmac_f32_dpp v221, v87, v147 row_shr:2 row_mask:0xf bank_mask:0xf
	v_exp_f32_e32 v217, v217
	v_fmac_f32_dpp v221, v103, v147 row_shl:14 row_mask:0xf bank_mask:0xf
	v_pk_add_f32 v[216:217], v[216:217], s[36:37]
	v_pk_mul_f32 v[222:223], v[218:219], s[34:35]
	v_rcp_f32_e32 v216, v216
	v_exp_f32_e32 v222, v222
	v_rcp_f32_e32 v217, v217
	v_exp_f32_e32 v223, v223
	v_pk_mul_f32 v[192:193], v[192:193], v[194:195]
	v_pk_add_f32 v[222:223], v[222:223], s[36:37]
	v_pk_mul_f32 v[92:93], v[192:193], v[216:217]
	v_rcp_f32_e32 v222, v222
	v_pk_fma_f32 v[192:193], v[108:109], v[136:137], v[140:141]
	v_rcp_f32_e32 v223, v223
	v_pk_fma_f32 v[194:195], v[100:101], v[152:153], v[156:157]
	v_pk_mul_f32 v[218:219], v[218:219], v[220:221]
	v_fmac_f32_dpp v192, v108, v132 row_shr:1 row_mask:0xf bank_mask:0xf
	v_pk_mul_f32 v[94:95], v[218:219], v[222:223]
	v_fmac_f32_dpp v192, v124, v132 row_shl:15 row_mask:0xf bank_mask:0xf
	v_pk_fma_f32 v[218:219], v[110:111], v[138:139], v[142:143]
	v_fmac_f32_dpp v192, v108, v128 row_shr:2 row_mask:0xf bank_mask:0xf
	v_pk_fma_f32 v[220:221], v[102:103], v[154:155], v[158:159]
	v_fmac_f32_dpp v192, v124, v128 row_shl:14 row_mask:0xf bank_mask:0xf
	v_fmac_f32_dpp v218, v110, v134 row_shr:1 row_mask:0xf bank_mask:0xf
	v_fmac_f32_dpp v193, v109, v133 row_shr:1 row_mask:0xf bank_mask:0xf
	v_fmac_f32_dpp v218, v126, v134 row_shl:15 row_mask:0xf bank_mask:0xf
	v_fmac_f32_dpp v193, v125, v133 row_shl:15 row_mask:0xf bank_mask:0xf
	v_fmac_f32_dpp v218, v110, v130 row_shr:2 row_mask:0xf bank_mask:0xf
	v_fmac_f32_dpp v193, v109, v129 row_shr:2 row_mask:0xf bank_mask:0xf
	v_fmac_f32_dpp v218, v126, v130 row_shl:14 row_mask:0xf bank_mask:0xf
	v_fmac_f32_dpp v193, v125, v129 row_shl:14 row_mask:0xf bank_mask:0xf
; __device__ __forceinline__ float sigmoidf_(float x) { return __builtin_amdgcn_rcpf(1.0f + __expf(-x)); }
; __device__ __forceinline__ void conv_phase(const Params& p, int layer) {
;     ...
;                 for (int e = 0; e < 8; ++e) {
;                     const float G = wg[0][e] * g2[e] + wg[1][e] * g1[e] + wg[2][e] * g0[e] + bg[e];
;                     const float V = wv[0][e] * v2[e] + wv[1][e] * v1[e] + wv[2][e] * v0[e] + bv[e];
;                     o[e] = G * sigmoidf_(G) * V;
	v_fmac_f32_dpp v219, v111, v135 row_shr:1 row_mask:0xf bank_mask:0xf
	v_fmac_f32_dpp v194, v100, v148 row_shr:1 row_mask:0xf bank_mask:0xf
	v_fmac_f32_dpp v219, v127, v135 row_shl:15 row_mask:0xf bank_mask:0xf
	v_fmac_f32_dpp v194, v116, v148 row_shl:15 row_mask:0xf bank_mask:0xf
	v_fmac_f32_dpp v219, v111, v131 row_shr:2 row_mask:0xf bank_mask:0xf
	v_fmac_f32_dpp v194, v100, v144 row_shr:2 row_mask:0xf bank_mask:0xf
	v_fmac_f32_dpp v219, v127, v131 row_shl:14 row_mask:0xf bank_mask:0xf
	v_fmac_f32_dpp v194, v116, v144 row_shl:14 row_mask:0xf bank_mask:0xf
	v_fmac_f32_dpp v220, v102, v150 row_shr:1 row_mask:0xf bank_mask:0xf
	v_fmac_f32_dpp v195, v101, v149 row_shr:1 row_mask:0xf bank_mask:0xf
	v_fmac_f32_dpp v220, v118, v150 row_shl:15 row_mask:0xf bank_mask:0xf
	v_fmac_f32_dpp v195, v117, v149 row_shl:15 row_mask:0xf bank_mask:0xf
	v_fmac_f32_dpp v220, v102, v146 row_shr:2 row_mask:0xf bank_mask:0xf
	v_fmac_f32_dpp v195, v101, v145 row_shr:2 row_mask:0xf bank_mask:0xf
	v_fmac_f32_dpp v220, v118, v146 row_shl:14 row_mask:0xf bank_mask:0xf
	v_fmac_f32_dpp v195, v117, v145 row_shl:14 row_mask:0xf bank_mask:0xf
	v_fmac_f32_dpp v221, v103, v151 row_shr:1 row_mask:0xf bank_mask:0xf
	v_pk_mul_f32 v[216:217], v[192:193], s[34:35]
	v_fmac_f32_dpp v221, v119, v151 row_shl:15 row_mask:0xf bank_mask:0xf
	v_exp_f32_e32 v216, v216
	v_fmac_f32_dpp v221, v103, v147 row_shr:2 row_mask:0xf bank_mask:0xf
	v_exp_f32_e32 v217, v217
	v_fmac_f32_dpp v221, v119, v147 row_shl:14 row_mask:0xf bank_mask:0xf
	v_pk_add_f32 v[216:217], v[216:217], s[36:37]
	v_pk_mul_f32 v[222:223], v[218:219], s[34:35]
	v_rcp_f32_e32 v216, v216
	v_exp_f32_e32 v222, v222
	v_rcp_f32_e32 v217, v217
	v_exp_f32_e32 v223, v223
	v_pk_mul_f32 v[192:193], v[192:193], v[194:195]
	v_pk_add_f32 v[222:223], v[222:223], s[36:37]
	v_pk_mul_f32 v[108:109], v[192:193], v[216:217]
	v_rcp_f32_e32 v222, v222
	v_pk_fma_f32 v[192:193], v[124:125], v[136:137], v[140:141]
	v_rcp_f32_e32 v223, v223
	v_pk_fma_f32 v[194:195], v[116:117], v[152:153], v[156:157]
	v_pk_mul_f32 v[218:219], v[218:219], v[220:221]
	v_fmac_f32_dpp v192, v124, v132 row_shr:1 row_mask:0xf bank_mask:0xf
	v_pk_mul_f32 v[110:111], v[218:219], v[222:223]
	v_fmac_f32_dpp v192, v124, v132 row_shl:15 row_mask:0xf bank_mask:0xf
	v_pk_fma_f32 v[218:219], v[126:127], v[138:139], v[142:143]
	v_fmac_f32_dpp v192, v124, v128 row_shr:2 row_mask:0xf bank_mask:0xf
	v_pk_fma_f32 v[220:221], v[118:119], v[154:155], v[158:159]
	v_fmac_f32_dpp v192, v124, v128 row_shl:14 row_mask:0xf bank_mask:0xf
	v_fmac_f32_dpp v218, v126, v134 row_shr:1 row_mask:0xf bank_mask:0xf
	v_fmac_f32_dpp v193, v125, v133 row_shr:1 row_mask:0xf bank_mask:0xf
	v_fmac_f32_dpp v218, v126, v134 row_shl:15 row_mask:0xf bank_mask:0xf
	v_fmac_f32_dpp v193, v125, v133 row_shl:15 row_mask:0xf bank_mask:0xf
	v_fmac_f32_dpp v218, v126, v130 row_shr:2 row_mask:0xf bank_mask:0xf
	v_fmac_f32_dpp v193, v125, v129 row_shr:2 row_mask:0xf bank_mask:0xf
	v_fmac_f32_dpp v218, v126, v130 row_shl:14 row_mask:0xf bank_mask:0xf
	v_fmac_f32_dpp v193, v125, v129 row_shl:14 row_mask:0xf bank_mask:0xf
	v_fmac_f32_dpp v219, v127, v135 row_shr:1 row_mask:0xf bank_mask:0xf
	v_fmac_f32_dpp v194, v116, v148 row_shr:1 row_mask:0xf bank_mask:0xf
	v_fmac_f32_dpp v219, v127, v135 row_shl:15 row_mask:0xf bank_mask:0xf
	v_fmac_f32_dpp v194, v116, v148 row_shl:15 row_mask:0xf bank_mask:0xf
	v_fmac_f32_dpp v219, v127, v131 row_shr:2 row_mask:0xf bank_mask:0xf
	v_fmac_f32_dpp v194, v116, v144 row_shr:2 row_mask:0xf bank_mask:0xf
	v_fmac_f32_dpp v219, v127, v131 row_shl:14 row_mask:0xf bank_mask:0xf
	v_fmac_f32_dpp v194, v116, v144 row_shl:14 row_mask:0xf bank_mask:0xf
	v_fmac_f32_dpp v220, v118, v150 row_shr:1 row_mask:0xf bank_mask:0xf
	v_fmac_f32_dpp v195, v117, v149 row_shr:1 row_mask:0xf bank_mask:0xf
	v_fmac_f32_dpp v220, v118, v150 row_shl:15 row_mask:0xf bank_mask:0xf
	v_fmac_f32_dpp v195, v117, v149 row_shl:15 row_mask:0xf bank_mask:0xf
	v_fmac_f32_dpp v220, v118, v146 row_shr:2 row_mask:0xf bank_mask:0xf
	v_fmac_f32_dpp v195, v117, v145 row_shr:2 row_mask:0xf bank_mask:0xf
	v_fmac_f32_dpp v220, v118, v146 row_shl:14 row_mask:0xf bank_mask:0xf
	v_fmac_f32_dpp v195, v117, v145 row_shl:14 row_mask:0xf bank_mask:0xf
	v_fmac_f32_dpp v221, v119, v151 row_shr:1 row_mask:0xf bank_mask:0xf
	v_pk_mul_f32 v[216:217], v[192:193], s[34:35]
	v_fmac_f32_dpp v221, v119, v151 row_shl:15 row_mask:0xf bank_mask:0xf
	v_exp_f32_e32 v216, v216
	v_fmac_f32_dpp v221, v119, v147 row_shr:2 row_mask:0xf bank_mask:0xf
	v_exp_f32_e32 v217, v217
	v_fmac_f32_dpp v221, v119, v147 row_shl:14 row_mask:0xf bank_mask:0xf
	v_pk_add_f32 v[216:217], v[216:217], s[36:37]
	v_pk_mul_f32 v[222:223], v[218:219], s[34:35]
	v_rcp_f32_e32 v216, v216
	v_exp_f32_e32 v222, v222
	v_rcp_f32_e32 v217, v217
	v_exp_f32_e32 v223, v223
	v_pk_mul_f32 v[192:193], v[192:193], v[194:195]
	v_pk_add_f32 v[222:223], v[222:223], s[36:37]
	v_pk_mul_f32 v[124:125], v[192:193], v[216:217]
	v_rcp_f32_e32 v222, v222
	v_pk_fma_f32 v[192:193], v[12:13], v[136:137], v[140:141]
	v_rcp_f32_e32 v223, v223
	v_pk_fma_f32 v[194:195], v[4:5], v[152:153], v[156:157]
	v_pk_mul_f32 v[218:219], v[218:219], v[220:221]
	v_fmac_f32_dpp v192, v12, v132 row_shr:1 row_mask:0xf bank_mask:0xf
	v_pk_mul_f32 v[126:127], v[218:219], v[222:223]
	v_fmac_f32_dpp v192, v28, v132 row_shl:15 row_mask:0xf bank_mask:0xf
	v_pk_fma_f32 v[218:219], v[14:15], v[138:139], v[142:143]
	v_fmac_f32_dpp v192, v12, v128 row_shr:2 row_mask:0xf bank_mask:0xf
	v_pk_fma_f32 v[220:221], v[6:7], v[154:155], v[158:159]
	v_fmac_f32_dpp v192, v28, v128 row_shl:14 row_mask:0xf bank_mask:0xf
	v_fmac_f32_dpp v218, v14, v134 row_shr:1 row_mask:0xf bank_mask:0xf
; __device__ __forceinline__ float sigmoidf_(float x) { return __builtin_amdgcn_rcpf(1.0f + __expf(-x)); }
; __device__ __forceinline__ void conv_phase(const Params& p, int layer) {
;     ...
;                 for (int e = 0; e < 8; ++e) {
;                     const float G = wg[0][e] * g2[e] + wg[1][e] * g1[e] + wg[2][e] * g0[e] + bg[e];
;                     const float V = wv[0][e] * v2[e] + wv[1][e] * v1[e] + wv[2][e] * v0[e] + bv[e];
;                     o[e] = G * sigmoidf_(G) * V;
	v_fmac_f32_dpp v193, v13, v133 row_shr:1 row_mask:0xf bank_mask:0xf
	v_fmac_f32_dpp v218, v30, v134 row_shl:15 row_mask:0xf bank_mask:0xf
	v_fmac_f32_dpp v193, v29, v133 row_shl:15 row_mask:0xf bank_mask:0xf
	v_fmac_f32_dpp v218, v14, v130 row_shr:2 row_mask:0xf bank_mask:0xf
	v_fmac_f32_dpp v193, v13, v129 row_shr:2 row_mask:0xf bank_mask:0xf
	v_fmac_f32_dpp v218, v30, v130 row_shl:14 row_mask:0xf bank_mask:0xf
	v_fmac_f32_dpp v193, v29, v129 row_shl:14 row_mask:0xf bank_mask:0xf
	v_fmac_f32_dpp v219, v15, v135 row_shr:1 row_mask:0xf bank_mask:0xf
	v_fmac_f32_dpp v194, v4, v148 row_shr:1 row_mask:0xf bank_mask:0xf
	v_fmac_f32_dpp v219, v31, v135 row_shl:15 row_mask:0xf bank_mask:0xf
	v_fmac_f32_dpp v194, v20, v148 row_shl:15 row_mask:0xf bank_mask:0xf
	v_fmac_f32_dpp v219, v15, v131 row_shr:2 row_mask:0xf bank_mask:0xf
	v_fmac_f32_dpp v194, v4, v144 row_shr:2 row_mask:0xf bank_mask:0xf
	v_fmac_f32_dpp v219, v31, v131 row_shl:14 row_mask:0xf bank_mask:0xf
	v_fmac_f32_dpp v194, v20, v144 row_shl:14 row_mask:0xf bank_mask:0xf
	v_fmac_f32_dpp v220, v6, v150 row_shr:1 row_mask:0xf bank_mask:0xf
	v_fmac_f32_dpp v195, v5, v149 row_shr:1 row_mask:0xf bank_mask:0xf
	v_fmac_f32_dpp v220, v22, v150 row_shl:15 row_mask:0xf bank_mask:0xf
	v_fmac_f32_dpp v195, v21, v149 row_shl:15 row_mask:0xf bank_mask:0xf
	v_fmac_f32_dpp v220, v6, v146 row_shr:2 row_mask:0xf bank_mask:0xf
	v_fmac_f32_dpp v195, v5, v145 row_shr:2 row_mask:0xf bank_mask:0xf
	v_fmac_f32_dpp v220, v22, v146 row_shl:14 row_mask:0xf bank_mask:0xf
	v_fmac_f32_dpp v195, v21, v145 row_shl:14 row_mask:0xf bank_mask:0xf
	v_fmac_f32_dpp v221, v7, v151 row_shr:1 row_mask:0xf bank_mask:0xf
	v_pk_mul_f32 v[216:217], v[192:193], s[34:35]
	v_fmac_f32_dpp v221, v23, v151 row_shl:15 row_mask:0xf bank_mask:0xf
	v_exp_f32_e32 v216, v216
	v_fmac_f32_dpp v221, v7, v147 row_shr:2 row_mask:0xf bank_mask:0xf
	v_exp_f32_e32 v217, v217
	v_fmac_f32_dpp v221, v23, v147 row_shl:14 row_mask:0xf bank_mask:0xf
	v_pk_add_f32 v[216:217], v[216:217], s[36:37]
	v_pk_mul_f32 v[222:223], v[218:219], s[34:35]
	v_rcp_f32_e32 v216, v216
	v_exp_f32_e32 v222, v222
	v_rcp_f32_e32 v217, v217
	v_exp_f32_e32 v223, v223
	v_pk_mul_f32 v[192:193], v[192:193], v[194:195]
	v_pk_add_f32 v[222:223], v[222:223], s[36:37]
	v_pk_mul_f32 v[12:13], v[192:193], v[216:217]
	v_rcp_f32_e32 v222, v222
	v_pk_fma_f32 v[192:193], v[28:29], v[136:137], v[140:141]
	v_rcp_f32_e32 v223, v223
	v_pk_fma_f32 v[194:195], v[20:21], v[152:153], v[156:157]
	v_pk_mul_f32 v[218:219], v[218:219], v[220:221]
	v_fmac_f32_dpp v192, v28, v132 row_shr:1 row_mask:0xf bank_mask:0xf
	v_pk_mul_f32 v[14:15], v[218:219], v[222:223]
	v_fmac_f32_dpp v192, v44, v132 row_shl:15 row_mask:0xf bank_mask:0xf
	v_pk_fma_f32 v[218:219], v[30:31], v[138:139], v[142:143]
	v_fmac_f32_dpp v192, v28, v128 row_shr:2 row_mask:0xf bank_mask:0xf
	v_pk_fma_f32 v[220:221], v[22:23], v[154:155], v[158:159]
	v_fmac_f32_dpp v192, v44, v128 row_shl:14 row_mask:0xf bank_mask:0xf
	v_fmac_f32_dpp v218, v30, v134 row_shr:1 row_mask:0xf bank_mask:0xf
	v_fmac_f32_dpp v193, v29, v133 row_shr:1 row_mask:0xf bank_mask:0xf
	v_fmac_f32_dpp v218, v46, v134 row_shl:15 row_mask:0xf bank_mask:0xf
	v_fmac_f32_dpp v193, v45, v133 row_shl:15 row_mask:0xf bank_mask:0xf
	v_fmac_f32_dpp v218, v30, v130 row_shr:2 row_mask:0xf bank_mask:0xf
	v_fmac_f32_dpp v193, v29, v129 row_shr:2 row_mask:0xf bank_mask:0xf
	v_fmac_f32_dpp v218, v46, v130 row_shl:14 row_mask:0xf bank_mask:0xf
	v_fmac_f32_dpp v193, v45, v129 row_shl:14 row_mask:0xf bank_mask:0xf
	v_fmac_f32_dpp v219, v31, v135 row_shr:1 row_mask:0xf bank_mask:0xf
	v_fmac_f32_dpp v194, v20, v148 row_shr:1 row_mask:0xf bank_mask:0xf
	v_fmac_f32_dpp v219, v47, v135 row_shl:15 row_mask:0xf bank_mask:0xf
	v_fmac_f32_dpp v194, v36, v148 row_shl:15 row_mask:0xf bank_mask:0xf
	v_fmac_f32_dpp v219, v31, v131 row_shr:2 row_mask:0xf bank_mask:0xf
	v_fmac_f32_dpp v194, v20, v144 row_shr:2 row_mask:0xf bank_mask:0xf
	v_fmac_f32_dpp v219, v47, v131 row_shl:14 row_mask:0xf bank_mask:0xf
	v_fmac_f32_dpp v194, v36, v144 row_shl:14 row_mask:0xf bank_mask:0xf
	v_fmac_f32_dpp v220, v22, v150 row_shr:1 row_mask:0xf bank_mask:0xf
	v_fmac_f32_dpp v195, v21, v149 row_shr:1 row_mask:0xf bank_mask:0xf
	v_fmac_f32_dpp v220, v38, v150 row_shl:15 row_mask:0xf bank_mask:0xf
	v_fmac_f32_dpp v195, v37, v149 row_shl:15 row_mask:0xf bank_mask:0xf
	v_fmac_f32_dpp v220, v22, v146 row_shr:2 row_mask:0xf bank_mask:0xf
	v_fmac_f32_dpp v195, v21, v145 row_shr:2 row_mask:0xf bank_mask:0xf
	v_fmac_f32_dpp v220, v38, v146 row_shl:14 row_mask:0xf bank_mask:0xf
	v_fmac_f32_dpp v195, v37, v145 row_shl:14 row_mask:0xf bank_mask:0xf
	v_fmac_f32_dpp v221, v23, v151 row_shr:1 row_mask:0xf bank_mask:0xf
	v_pk_mul_f32 v[216:217], v[192:193], s[34:35]
	v_fmac_f32_dpp v221, v39, v151 row_shl:15 row_mask:0xf bank_mask:0xf
	v_exp_f32_e32 v216, v216
	v_fmac_f32_dpp v221, v23, v147 row_shr:2 row_mask:0xf bank_mask:0xf
	v_exp_f32_e32 v217, v217
	v_fmac_f32_dpp v221, v39, v147 row_shl:14 row_mask:0xf bank_mask:0xf
	v_pk_add_f32 v[216:217], v[216:217], s[36:37]
	v_pk_mul_f32 v[222:223], v[218:219], s[34:35]
	v_rcp_f32_e32 v216, v216
	v_exp_f32_e32 v222, v222
	v_rcp_f32_e32 v217, v217
	v_exp_f32_e32 v223, v223
	v_pk_mul_f32 v[192:193], v[192:193], v[194:195]
	v_pk_add_f32 v[222:223], v[222:223], s[36:37]
	v_pk_mul_f32 v[28:29], v[192:193], v[216:217]
	v_rcp_f32_e32 v222, v222
	v_pk_fma_f32 v[192:193], v[44:45], v[136:137], v[140:141]
	v_rcp_f32_e32 v223, v223
	v_pk_fma_f32 v[194:195], v[36:37], v[152:153], v[156:157]
	v_pk_mul_f32 v[218:219], v[218:219], v[220:221]
	v_fmac_f32_dpp v192, v44, v132 row_shr:1 row_mask:0xf bank_mask:0xf
; __device__ __forceinline__ float sigmoidf_(float x) { return __builtin_amdgcn_rcpf(1.0f + __expf(-x)); }
; __device__ __forceinline__ void conv_phase(const Params& p, int layer) {
;     ...
;                 for (int e = 0; e < 8; ++e) {
;                     const float G = wg[0][e] * g2[e] + wg[1][e] * g1[e] + wg[2][e] * g0[e] + bg[e];
;                     const float V = wv[0][e] * v2[e] + wv[1][e] * v1[e] + wv[2][e] * v0[e] + bv[e];
;                     o[e] = G * sigmoidf_(G) * V;
	v_pk_mul_f32 v[30:31], v[218:219], v[222:223]
	v_fmac_f32_dpp v192, v60, v132 row_shl:15 row_mask:0xf bank_mask:0xf
	v_pk_fma_f32 v[218:219], v[46:47], v[138:139], v[142:143]
	v_fmac_f32_dpp v192, v44, v128 row_shr:2 row_mask:0xf bank_mask:0xf
	v_pk_fma_f32 v[220:221], v[38:39], v[154:155], v[158:159]
	v_fmac_f32_dpp v192, v60, v128 row_shl:14 row_mask:0xf bank_mask:0xf
	v_fmac_f32_dpp v218, v46, v134 row_shr:1 row_mask:0xf bank_mask:0xf
	v_fmac_f32_dpp v193, v45, v133 row_shr:1 row_mask:0xf bank_mask:0xf
	v_fmac_f32_dpp v218, v62, v134 row_shl:15 row_mask:0xf bank_mask:0xf
	v_fmac_f32_dpp v193, v61, v133 row_shl:15 row_mask:0xf bank_mask:0xf
	v_fmac_f32_dpp v218, v46, v130 row_shr:2 row_mask:0xf bank_mask:0xf
	v_fmac_f32_dpp v193, v45, v129 row_shr:2 row_mask:0xf bank_mask:0xf
	v_fmac_f32_dpp v218, v62, v130 row_shl:14 row_mask:0xf bank_mask:0xf
	v_fmac_f32_dpp v193, v61, v129 row_shl:14 row_mask:0xf bank_mask:0xf
	v_fmac_f32_dpp v219, v47, v135 row_shr:1 row_mask:0xf bank_mask:0xf
	v_fmac_f32_dpp v194, v36, v148 row_shr:1 row_mask:0xf bank_mask:0xf
	v_fmac_f32_dpp v219, v63, v135 row_shl:15 row_mask:0xf bank_mask:0xf
	v_fmac_f32_dpp v194, v52, v148 row_shl:15 row_mask:0xf bank_mask:0xf
	v_fmac_f32_dpp v219, v47, v131 row_shr:2 row_mask:0xf bank_mask:0xf
	v_fmac_f32_dpp v194, v36, v144 row_shr:2 row_mask:0xf bank_mask:0xf
	v_fmac_f32_dpp v219, v63, v131 row_shl:14 row_mask:0xf bank_mask:0xf
	v_fmac_f32_dpp v194, v52, v144 row_shl:14 row_mask:0xf bank_mask:0xf
	v_fmac_f32_dpp v220, v38, v150 row_shr:1 row_mask:0xf bank_mask:0xf
	v_fmac_f32_dpp v195, v37, v149 row_shr:1 row_mask:0xf bank_mask:0xf
	v_fmac_f32_dpp v220, v54, v150 row_shl:15 row_mask:0xf bank_mask:0xf
	v_fmac_f32_dpp v195, v53, v149 row_shl:15 row_mask:0xf bank_mask:0xf
	v_fmac_f32_dpp v220, v38, v146 row_shr:2 row_mask:0xf bank_mask:0xf
	v_fmac_f32_dpp v195, v37, v145 row_shr:2 row_mask:0xf bank_mask:0xf
	v_fmac_f32_dpp v220, v54, v146 row_shl:14 row_mask:0xf bank_mask:0xf
	v_fmac_f32_dpp v195, v53, v145 row_shl:14 row_mask:0xf bank_mask:0xf
	v_fmac_f32_dpp v221, v39, v151 row_shr:1 row_mask:0xf bank_mask:0xf
	v_pk_mul_f32 v[216:217], v[192:193], s[34:35]
	v_fmac_f32_dpp v221, v55, v151 row_shl:15 row_mask:0xf bank_mask:0xf
	v_exp_f32_e32 v216, v216
	v_fmac_f32_dpp v221, v39, v147 row_shr:2 row_mask:0xf bank_mask:0xf
	v_exp_f32_e32 v217, v217
	v_fmac_f32_dpp v221, v55, v147 row_shl:14 row_mask:0xf bank_mask:0xf
	v_pk_add_f32 v[216:217], v[216:217], s[36:37]
	v_pk_mul_f32 v[222:223], v[218:219], s[34:35]
	v_rcp_f32_e32 v216, v216
	v_exp_f32_e32 v222, v222
	v_rcp_f32_e32 v217, v217
	v_exp_f32_e32 v223, v223
	v_pk_mul_f32 v[192:193], v[192:193], v[194:195]
	v_pk_add_f32 v[222:223], v[222:223], s[36:37]
	v_pk_mul_f32 v[44:45], v[192:193], v[216:217]
	v_rcp_f32_e32 v222, v222
	v_pk_fma_f32 v[192:193], v[60:61], v[136:137], v[140:141]
	v_rcp_f32_e32 v223, v223
	v_pk_fma_f32 v[194:195], v[52:53], v[152:153], v[156:157]
	v_pk_mul_f32 v[218:219], v[218:219], v[220:221]
	v_fmac_f32_dpp v192, v60, v132 row_shr:1 row_mask:0xf bank_mask:0xf
	v_pk_mul_f32 v[46:47], v[218:219], v[222:223]
	v_fmac_f32_dpp v192, v60, v132 row_shl:15 row_mask:0xf bank_mask:0xf
	v_pk_fma_f32 v[218:219], v[62:63], v[138:139], v[142:143]
	v_fmac_f32_dpp v192, v60, v128 row_shr:2 row_mask:0xf bank_mask:0xf
	v_pk_fma_f32 v[220:221], v[54:55], v[154:155], v[158:159]
	v_fmac_f32_dpp v192, v60, v128 row_shl:14 row_mask:0xf bank_mask:0xf
	v_fmac_f32_dpp v218, v62, v134 row_shr:1 row_mask:0xf bank_mask:0xf
	v_fmac_f32_dpp v193, v61, v133 row_shr:1 row_mask:0xf bank_mask:0xf
	v_fmac_f32_dpp v218, v62, v134 row_shl:15 row_mask:0xf bank_mask:0xf
	v_fmac_f32_dpp v193, v61, v133 row_shl:15 row_mask:0xf bank_mask:0xf
	v_fmac_f32_dpp v218, v62, v130 row_shr:2 row_mask:0xf bank_mask:0xf
	v_fmac_f32_dpp v193, v61, v129 row_shr:2 row_mask:0xf bank_mask:0xf
	v_fmac_f32_dpp v218, v62, v130 row_shl:14 row_mask:0xf bank_mask:0xf
	v_fmac_f32_dpp v193, v61, v129 row_shl:14 row_mask:0xf bank_mask:0xf
	v_fmac_f32_dpp v219, v63, v135 row_shr:1 row_mask:0xf bank_mask:0xf
	v_fmac_f32_dpp v194, v52, v148 row_shr:1 row_mask:0xf bank_mask:0xf
	v_fmac_f32_dpp v219, v63, v135 row_shl:15 row_mask:0xf bank_mask:0xf
	v_fmac_f32_dpp v194, v52, v148 row_shl:15 row_mask:0xf bank_mask:0xf
	v_fmac_f32_dpp v219, v63, v131 row_shr:2 row_mask:0xf bank_mask:0xf
	v_fmac_f32_dpp v194, v52, v144 row_shr:2 row_mask:0xf bank_mask:0xf
	v_fmac_f32_dpp v219, v63, v131 row_shl:14 row_mask:0xf bank_mask:0xf
	v_fmac_f32_dpp v194, v52, v144 row_shl:14 row_mask:0xf bank_mask:0xf
	v_fmac_f32_dpp v220, v54, v150 row_shr:1 row_mask:0xf bank_mask:0xf
	v_fmac_f32_dpp v195, v53, v149 row_shr:1 row_mask:0xf bank_mask:0xf
	v_fmac_f32_dpp v220, v54, v150 row_shl:15 row_mask:0xf bank_mask:0xf
	v_fmac_f32_dpp v195, v53, v149 row_shl:15 row_mask:0xf bank_mask:0xf
	v_fmac_f32_dpp v220, v54, v146 row_shr:2 row_mask:0xf bank_mask:0xf
	v_fmac_f32_dpp v195, v53, v145 row_shr:2 row_mask:0xf bank_mask:0xf
	v_fmac_f32_dpp v220, v54, v146 row_shl:14 row_mask:0xf bank_mask:0xf
	v_fmac_f32_dpp v195, v53, v145 row_shl:14 row_mask:0xf bank_mask:0xf
	v_fmac_f32_dpp v221, v55, v151 row_shr:1 row_mask:0xf bank_mask:0xf
	v_pk_mul_f32 v[216:217], v[192:193], s[34:35]
	v_fmac_f32_dpp v221, v55, v151 row_shl:15 row_mask:0xf bank_mask:0xf
	v_exp_f32_e32 v216, v216
	v_fmac_f32_dpp v221, v55, v147 row_shr:2 row_mask:0xf bank_mask:0xf
	v_exp_f32_e32 v217, v217
	v_fmac_f32_dpp v221, v55, v147 row_shl:14 row_mask:0xf bank_mask:0xf
	v_pk_add_f32 v[216:217], v[216:217], s[36:37]
	v_pk_mul_f32 v[222:223], v[218:219], s[34:35]
	v_rcp_f32_e32 v216, v216
	v_exp_f32_e32 v222, v222
	v_rcp_f32_e32 v217, v217
	v_exp_f32_e32 v223, v223
	v_pk_mul_f32 v[192:193], v[192:193], v[194:195]
	v_pk_add_f32 v[222:223], v[222:223], s[36:37]
	v_pk_mul_f32 v[60:61], v[192:193], v[216:217]
	v_rcp_f32_e32 v222, v222
	v_rcp_f32_e32 v223, v223
	v_pk_mul_f32 v[218:219], v[218:219], v[220:221]
	s_nop 0
	v_pk_mul_f32 v[62:63], v[218:219], v[222:223]
	s_waitcnt vmcnt(0)
; __device__ __forceinline__ float sigmoidf_(float x) { return __builtin_amdgcn_rcpf(1.0f + __expf(-x)); }
; __device__ __forceinline__ void conv_phase(const Params& p, int layer) {
;     ...
;                 for (int e = 0; e < 8; ++e) {
;                     const float G = wg[0][e] * g2[e] + wg[1][e] * g1[e] + wg[2][e] * g0[e] + bg[e];
;                     const float V = wv[0][e] * v2[e] + wv[1][e] * v1[e] + wv[2][e] * v0[e] + bv[e];
;                     o[e] = G * sigmoidf_(G) * V;
	v_pk_fma_f32 v[192:193], v[72:73], v[168:169], v[172:173]
	v_pk_fma_f32 v[194:195], v[64:65], v[184:185], v[188:189]
	v_fmac_f32_dpp v192, v72, v164 row_shr:1 row_mask:0xf bank_mask:0xf
	v_fmac_f32_dpp v192, v88, v164 row_shl:15 row_mask:0xf bank_mask:0xf
	v_pk_fma_f32 v[218:219], v[74:75], v[170:171], v[174:175]
	v_fmac_f32_dpp v192, v72, v160 row_shr:2 row_mask:0xf bank_mask:0xf
	v_pk_fma_f32 v[220:221], v[66:67], v[186:187], v[190:191]
	v_fmac_f32_dpp v192, v88, v160 row_shl:14 row_mask:0xf bank_mask:0xf
	v_fmac_f32_dpp v218, v74, v166 row_shr:1 row_mask:0xf bank_mask:0xf
	v_fmac_f32_dpp v193, v73, v165 row_shr:1 row_mask:0xf bank_mask:0xf
	v_fmac_f32_dpp v218, v90, v166 row_shl:15 row_mask:0xf bank_mask:0xf
	v_fmac_f32_dpp v193, v89, v165 row_shl:15 row_mask:0xf bank_mask:0xf
	v_fmac_f32_dpp v218, v74, v162 row_shr:2 row_mask:0xf bank_mask:0xf
	v_fmac_f32_dpp v193, v73, v161 row_shr:2 row_mask:0xf bank_mask:0xf
	v_fmac_f32_dpp v218, v90, v162 row_shl:14 row_mask:0xf bank_mask:0xf
	v_fmac_f32_dpp v193, v89, v161 row_shl:14 row_mask:0xf bank_mask:0xf
	v_fmac_f32_dpp v219, v75, v167 row_shr:1 row_mask:0xf bank_mask:0xf
	v_fmac_f32_dpp v194, v64, v180 row_shr:1 row_mask:0xf bank_mask:0xf
	v_fmac_f32_dpp v219, v91, v167 row_shl:15 row_mask:0xf bank_mask:0xf
	v_fmac_f32_dpp v194, v80, v180 row_shl:15 row_mask:0xf bank_mask:0xf
	v_fmac_f32_dpp v219, v75, v163 row_shr:2 row_mask:0xf bank_mask:0xf
	v_fmac_f32_dpp v194, v64, v176 row_shr:2 row_mask:0xf bank_mask:0xf
	v_fmac_f32_dpp v219, v91, v163 row_shl:14 row_mask:0xf bank_mask:0xf
	v_fmac_f32_dpp v194, v80, v176 row_shl:14 row_mask:0xf bank_mask:0xf
	v_fmac_f32_dpp v220, v66, v182 row_shr:1 row_mask:0xf bank_mask:0xf
	v_fmac_f32_dpp v195, v65, v181 row_shr:1 row_mask:0xf bank_mask:0xf
	v_fmac_f32_dpp v220, v82, v182 row_shl:15 row_mask:0xf bank_mask:0xf
	v_fmac_f32_dpp v195, v81, v181 row_shl:15 row_mask:0xf bank_mask:0xf
	v_fmac_f32_dpp v220, v66, v178 row_shr:2 row_mask:0xf bank_mask:0xf
	v_fmac_f32_dpp v195, v65, v177 row_shr:2 row_mask:0xf bank_mask:0xf
	v_fmac_f32_dpp v220, v82, v178 row_shl:14 row_mask:0xf bank_mask:0xf
	v_fmac_f32_dpp v195, v81, v177 row_shl:14 row_mask:0xf bank_mask:0xf
	v_fmac_f32_dpp v221, v67, v183 row_shr:1 row_mask:0xf bank_mask:0xf
	v_pk_mul_f32 v[216:217], v[192:193], s[34:35]
	v_fmac_f32_dpp v221, v83, v183 row_shl:15 row_mask:0xf bank_mask:0xf
	v_exp_f32_e32 v216, v216
	v_fmac_f32_dpp v221, v67, v179 row_shr:2 row_mask:0xf bank_mask:0xf
	v_exp_f32_e32 v217, v217
	v_fmac_f32_dpp v221, v83, v179 row_shl:14 row_mask:0xf bank_mask:0xf
	v_pk_add_f32 v[216:217], v[216:217], s[36:37]
	v_pk_mul_f32 v[222:223], v[218:219], s[34:35]
	v_rcp_f32_e32 v216, v216
	v_exp_f32_e32 v222, v222
	v_rcp_f32_e32 v217, v217
	v_exp_f32_e32 v223, v223
	v_pk_mul_f32 v[192:193], v[192:193], v[194:195]
	v_pk_add_f32 v[222:223], v[222:223], s[36:37]
	v_pk_mul_f32 v[72:73], v[192:193], v[216:217]
	v_rcp_f32_e32 v222, v222
	v_pk_fma_f32 v[192:193], v[88:89], v[168:169], v[172:173]
	v_rcp_f32_e32 v223, v223
	v_pk_fma_f32 v[194:195], v[80:81], v[184:185], v[188:189]
	v_pk_mul_f32 v[218:219], v[218:219], v[220:221]
	v_fmac_f32_dpp v192, v88, v164 row_shr:1 row_mask:0xf bank_mask:0xf
	v_pk_mul_f32 v[74:75], v[218:219], v[222:223]
	v_fmac_f32_dpp v192, v104, v164 row_shl:15 row_mask:0xf bank_mask:0xf
	v_pk_fma_f32 v[218:219], v[90:91], v[170:171], v[174:175]
	v_fmac_f32_dpp v192, v88, v160 row_shr:2 row_mask:0xf bank_mask:0xf
	v_pk_fma_f32 v[220:221], v[82:83], v[186:187], v[190:191]
	v_fmac_f32_dpp v192, v104, v160 row_shl:14 row_mask:0xf bank_mask:0xf
	v_fmac_f32_dpp v218, v90, v166 row_shr:1 row_mask:0xf bank_mask:0xf
	v_fmac_f32_dpp v193, v89, v165 row_shr:1 row_mask:0xf bank_mask:0xf
	v_fmac_f32_dpp v218, v106, v166 row_shl:15 row_mask:0xf bank_mask:0xf
	v_fmac_f32_dpp v193, v105, v165 row_shl:15 row_mask:0xf bank_mask:0xf
	v_fmac_f32_dpp v218, v90, v162 row_shr:2 row_mask:0xf bank_mask:0xf
	v_fmac_f32_dpp v193, v89, v161 row_shr:2 row_mask:0xf bank_mask:0xf
	v_fmac_f32_dpp v218, v106, v162 row_shl:14 row_mask:0xf bank_mask:0xf
	v_fmac_f32_dpp v193, v105, v161 row_shl:14 row_mask:0xf bank_mask:0xf
	v_fmac_f32_dpp v219, v91, v167 row_shr:1 row_mask:0xf bank_mask:0xf
	v_fmac_f32_dpp v194, v80, v180 row_shr:1 row_mask:0xf bank_mask:0xf
	v_fmac_f32_dpp v219, v107, v167 row_shl:15 row_mask:0xf bank_mask:0xf
	v_fmac_f32_dpp v194, v96, v180 row_shl:15 row_mask:0xf bank_mask:0xf
	v_fmac_f32_dpp v219, v91, v163 row_shr:2 row_mask:0xf bank_mask:0xf
	v_fmac_f32_dpp v194, v80, v176 row_shr:2 row_mask:0xf bank_mask:0xf
	v_fmac_f32_dpp v219, v107, v163 row_shl:14 row_mask:0xf bank_mask:0xf
	v_fmac_f32_dpp v194, v96, v176 row_shl:14 row_mask:0xf bank_mask:0xf
	v_fmac_f32_dpp v220, v82, v182 row_shr:1 row_mask:0xf bank_mask:0xf
	v_fmac_f32_dpp v195, v81, v181 row_shr:1 row_mask:0xf bank_mask:0xf
	v_fmac_f32_dpp v220, v98, v182 row_shl:15 row_mask:0xf bank_mask:0xf
	v_fmac_f32_dpp v195, v97, v181 row_shl:15 row_mask:0xf bank_mask:0xf
	v_fmac_f32_dpp v220, v82, v178 row_shr:2 row_mask:0xf bank_mask:0xf
	v_fmac_f32_dpp v195, v81, v177 row_shr:2 row_mask:0xf bank_mask:0xf
	v_fmac_f32_dpp v220, v98, v178 row_shl:14 row_mask:0xf bank_mask:0xf
	v_fmac_f32_dpp v195, v97, v177 row_shl:14 row_mask:0xf bank_mask:0xf
	v_fmac_f32_dpp v221, v83, v183 row_shr:1 row_mask:0xf bank_mask:0xf
	v_pk_mul_f32 v[216:217], v[192:193], s[34:35]
	v_fmac_f32_dpp v221, v99, v183 row_shl:15 row_mask:0xf bank_mask:0xf
	v_exp_f32_e32 v216, v216
	v_fmac_f32_dpp v221, v83, v179 row_shr:2 row_mask:0xf bank_mask:0xf
	v_exp_f32_e32 v217, v217
	v_fmac_f32_dpp v221, v99, v179 row_shl:14 row_mask:0xf bank_mask:0xf
	v_pk_add_f32 v[216:217], v[216:217], s[36:37]
; __device__ __forceinline__ float sigmoidf_(float x) { return __builtin_amdgcn_rcpf(1.0f + __expf(-x)); }
; __device__ __forceinline__ void conv_phase(const Params& p, int layer) {
;     ...
;                 for (int e = 0; e < 8; ++e) {
;                     const float G = wg[0][e] * g2[e] + wg[1][e] * g1[e] + wg[2][e] * g0[e] + bg[e];
;                     const float V = wv[0][e] * v2[e] + wv[1][e] * v1[e] + wv[2][e] * v0[e] + bv[e];
;                     o[e] = G * sigmoidf_(G) * V;
	v_pk_mul_f32 v[222:223], v[218:219], s[34:35]
	v_rcp_f32_e32 v216, v216
	v_exp_f32_e32 v222, v222
	v_rcp_f32_e32 v217, v217
	v_exp_f32_e32 v223, v223
	v_pk_mul_f32 v[192:193], v[192:193], v[194:195]
	v_pk_add_f32 v[222:223], v[222:223], s[36:37]
	v_pk_mul_f32 v[88:89], v[192:193], v[216:217]
	v_rcp_f32_e32 v222, v222
	v_pk_fma_f32 v[192:193], v[104:105], v[168:169], v[172:173]
	v_rcp_f32_e32 v223, v223
	v_pk_fma_f32 v[194:195], v[96:97], v[184:185], v[188:189]
	v_pk_mul_f32 v[218:219], v[218:219], v[220:221]
	v_fmac_f32_dpp v192, v104, v164 row_shr:1 row_mask:0xf bank_mask:0xf
	v_pk_mul_f32 v[90:91], v[218:219], v[222:223]
	v_fmac_f32_dpp v192, v120, v164 row_shl:15 row_mask:0xf bank_mask:0xf
	v_pk_fma_f32 v[218:219], v[106:107], v[170:171], v[174:175]
	v_fmac_f32_dpp v192, v104, v160 row_shr:2 row_mask:0xf bank_mask:0xf
	v_pk_fma_f32 v[220:221], v[98:99], v[186:187], v[190:191]
	v_fmac_f32_dpp v192, v120, v160 row_shl:14 row_mask:0xf bank_mask:0xf
	v_fmac_f32_dpp v218, v106, v166 row_shr:1 row_mask:0xf bank_mask:0xf
	v_fmac_f32_dpp v193, v105, v165 row_shr:1 row_mask:0xf bank_mask:0xf
	v_fmac_f32_dpp v218, v122, v166 row_shl:15 row_mask:0xf bank_mask:0xf
	v_fmac_f32_dpp v193, v121, v165 row_shl:15 row_mask:0xf bank_mask:0xf
	v_fmac_f32_dpp v218, v106, v162 row_shr:2 row_mask:0xf bank_mask:0xf
	v_fmac_f32_dpp v193, v105, v161 row_shr:2 row_mask:0xf bank_mask:0xf
	v_fmac_f32_dpp v218, v122, v162 row_shl:14 row_mask:0xf bank_mask:0xf
	v_fmac_f32_dpp v193, v121, v161 row_shl:14 row_mask:0xf bank_mask:0xf
	v_fmac_f32_dpp v219, v107, v167 row_shr:1 row_mask:0xf bank_mask:0xf
	v_fmac_f32_dpp v194, v96, v180 row_shr:1 row_mask:0xf bank_mask:0xf
	v_fmac_f32_dpp v219, v123, v167 row_shl:15 row_mask:0xf bank_mask:0xf
	v_fmac_f32_dpp v194, v112, v180 row_shl:15 row_mask:0xf bank_mask:0xf
	v_fmac_f32_dpp v219, v107, v163 row_shr:2 row_mask:0xf bank_mask:0xf
	v_fmac_f32_dpp v194, v96, v176 row_shr:2 row_mask:0xf bank_mask:0xf
	v_fmac_f32_dpp v219, v123, v163 row_shl:14 row_mask:0xf bank_mask:0xf
	v_fmac_f32_dpp v194, v112, v176 row_shl:14 row_mask:0xf bank_mask:0xf
	v_fmac_f32_dpp v220, v98, v182 row_shr:1 row_mask:0xf bank_mask:0xf
	v_fmac_f32_dpp v195, v97, v181 row_shr:1 row_mask:0xf bank_mask:0xf
	v_fmac_f32_dpp v220, v114, v182 row_shl:15 row_mask:0xf bank_mask:0xf
	v_fmac_f32_dpp v195, v113, v181 row_shl:15 row_mask:0xf bank_mask:0xf
	v_fmac_f32_dpp v220, v98, v178 row_shr:2 row_mask:0xf bank_mask:0xf
	v_fmac_f32_dpp v195, v97, v177 row_shr:2 row_mask:0xf bank_mask:0xf
	v_fmac_f32_dpp v220, v114, v178 row_shl:14 row_mask:0xf bank_mask:0xf
	v_fmac_f32_dpp v195, v113, v177 row_shl:14 row_mask:0xf bank_mask:0xf
	v_fmac_f32_dpp v221, v99, v183 row_shr:1 row_mask:0xf bank_mask:0xf
	v_pk_mul_f32 v[216:217], v[192:193], s[34:35]
	v_fmac_f32_dpp v221, v115, v183 row_shl:15 row_mask:0xf bank_mask:0xf
	v_exp_f32_e32 v216, v216
	v_fmac_f32_dpp v221, v99, v179 row_shr:2 row_mask:0xf bank_mask:0xf
	v_exp_f32_e32 v217, v217
	v_fmac_f32_dpp v221, v115, v179 row_shl:14 row_mask:0xf bank_mask:0xf
	v_pk_add_f32 v[216:217], v[216:217], s[36:37]
	v_pk_mul_f32 v[222:223], v[218:219], s[34:35]
	v_rcp_f32_e32 v216, v216
	v_exp_f32_e32 v222, v222
	v_rcp_f32_e32 v217, v217
	v_exp_f32_e32 v223, v223
	v_pk_mul_f32 v[192:193], v[192:193], v[194:195]
	v_pk_add_f32 v[222:223], v[222:223], s[36:37]
	v_pk_mul_f32 v[104:105], v[192:193], v[216:217]
	v_rcp_f32_e32 v222, v222
	v_pk_fma_f32 v[192:193], v[120:121], v[168:169], v[172:173]
	v_rcp_f32_e32 v223, v223
	v_pk_fma_f32 v[194:195], v[112:113], v[184:185], v[188:189]
	v_pk_mul_f32 v[218:219], v[218:219], v[220:221]
	v_fmac_f32_dpp v192, v120, v164 row_shr:1 row_mask:0xf bank_mask:0xf
	v_pk_mul_f32 v[106:107], v[218:219], v[222:223]
	v_fmac_f32_dpp v192, v120, v164 row_shl:15 row_mask:0xf bank_mask:0xf
	v_pk_fma_f32 v[218:219], v[122:123], v[170:171], v[174:175]
	v_fmac_f32_dpp v192, v120, v160 row_shr:2 row_mask:0xf bank_mask:0xf
	v_pk_fma_f32 v[220:221], v[114:115], v[186:187], v[190:191]
	v_fmac_f32_dpp v192, v120, v160 row_shl:14 row_mask:0xf bank_mask:0xf
	v_fmac_f32_dpp v218, v122, v166 row_shr:1 row_mask:0xf bank_mask:0xf
	v_fmac_f32_dpp v193, v121, v165 row_shr:1 row_mask:0xf bank_mask:0xf
	v_fmac_f32_dpp v218, v122, v166 row_shl:15 row_mask:0xf bank_mask:0xf
	v_fmac_f32_dpp v193, v121, v165 row_shl:15 row_mask:0xf bank_mask:0xf
	v_fmac_f32_dpp v218, v122, v162 row_shr:2 row_mask:0xf bank_mask:0xf
	v_fmac_f32_dpp v193, v121, v161 row_shr:2 row_mask:0xf bank_mask:0xf
	v_fmac_f32_dpp v218, v122, v162 row_shl:14 row_mask:0xf bank_mask:0xf
	v_fmac_f32_dpp v193, v121, v161 row_shl:14 row_mask:0xf bank_mask:0xf
	v_fmac_f32_dpp v219, v123, v167 row_shr:1 row_mask:0xf bank_mask:0xf
	v_fmac_f32_dpp v194, v112, v180 row_shr:1 row_mask:0xf bank_mask:0xf
	v_fmac_f32_dpp v219, v123, v167 row_shl:15 row_mask:0xf bank_mask:0xf
	v_fmac_f32_dpp v194, v112, v180 row_shl:15 row_mask:0xf bank_mask:0xf
	v_fmac_f32_dpp v219, v123, v163 row_shr:2 row_mask:0xf bank_mask:0xf
	v_fmac_f32_dpp v194, v112, v176 row_shr:2 row_mask:0xf bank_mask:0xf
	v_fmac_f32_dpp v219, v123, v163 row_shl:14 row_mask:0xf bank_mask:0xf
	v_fmac_f32_dpp v194, v112, v176 row_shl:14 row_mask:0xf bank_mask:0xf
	v_fmac_f32_dpp v220, v114, v182 row_shr:1 row_mask:0xf bank_mask:0xf
	v_fmac_f32_dpp v195, v113, v181 row_shr:1 row_mask:0xf bank_mask:0xf
	v_fmac_f32_dpp v220, v114, v182 row_shl:15 row_mask:0xf bank_mask:0xf
	v_fmac_f32_dpp v195, v113, v181 row_shl:15 row_mask:0xf bank_mask:0xf
	v_fmac_f32_dpp v220, v114, v178 row_shr:2 row_mask:0xf bank_mask:0xf
	v_fmac_f32_dpp v195, v113, v177 row_shr:2 row_mask:0xf bank_mask:0xf
	v_fmac_f32_dpp v220, v114, v178 row_shl:14 row_mask:0xf bank_mask:0xf
; __device__ __forceinline__ float sigmoidf_(float x) { return __builtin_amdgcn_rcpf(1.0f + __expf(-x)); }
; __device__ __forceinline__ void conv_phase(const Params& p, int layer) {
;     ...
;                 for (int e = 0; e < 8; ++e) {
;                     const float G = wg[0][e] * g2[e] + wg[1][e] * g1[e] + wg[2][e] * g0[e] + bg[e];
;                     const float V = wv[0][e] * v2[e] + wv[1][e] * v1[e] + wv[2][e] * v0[e] + bv[e];
;                     o[e] = G * sigmoidf_(G) * V;
	v_fmac_f32_dpp v195, v113, v177 row_shl:14 row_mask:0xf bank_mask:0xf
	v_fmac_f32_dpp v221, v115, v183 row_shr:1 row_mask:0xf bank_mask:0xf
	v_pk_mul_f32 v[216:217], v[192:193], s[34:35]
	v_fmac_f32_dpp v221, v115, v183 row_shl:15 row_mask:0xf bank_mask:0xf
	v_exp_f32_e32 v216, v216
	v_fmac_f32_dpp v221, v115, v179 row_shr:2 row_mask:0xf bank_mask:0xf
	v_exp_f32_e32 v217, v217
	v_fmac_f32_dpp v221, v115, v179 row_shl:14 row_mask:0xf bank_mask:0xf
	v_pk_add_f32 v[216:217], v[216:217], s[36:37]
	v_pk_mul_f32 v[222:223], v[218:219], s[34:35]
	v_rcp_f32_e32 v216, v216
	v_exp_f32_e32 v222, v222
	v_rcp_f32_e32 v217, v217
	v_exp_f32_e32 v223, v223
	v_pk_mul_f32 v[192:193], v[192:193], v[194:195]
	v_pk_add_f32 v[222:223], v[222:223], s[36:37]
	v_pk_mul_f32 v[120:121], v[192:193], v[216:217]
	v_rcp_f32_e32 v222, v222
	v_pk_fma_f32 v[192:193], v[8:9], v[168:169], v[172:173]
	v_rcp_f32_e32 v223, v223
	v_pk_fma_f32 v[194:195], v[0:1], v[184:185], v[188:189]
	v_pk_mul_f32 v[218:219], v[218:219], v[220:221]
	v_fmac_f32_dpp v192, v8, v164 row_shr:1 row_mask:0xf bank_mask:0xf
	v_pk_mul_f32 v[122:123], v[218:219], v[222:223]
	v_fmac_f32_dpp v192, v24, v164 row_shl:15 row_mask:0xf bank_mask:0xf
	v_pk_fma_f32 v[218:219], v[10:11], v[170:171], v[174:175]
	v_fmac_f32_dpp v192, v8, v160 row_shr:2 row_mask:0xf bank_mask:0xf
	v_pk_fma_f32 v[220:221], v[2:3], v[186:187], v[190:191]
	v_fmac_f32_dpp v192, v24, v160 row_shl:14 row_mask:0xf bank_mask:0xf
	v_fmac_f32_dpp v218, v10, v166 row_shr:1 row_mask:0xf bank_mask:0xf
	v_fmac_f32_dpp v193, v9, v165 row_shr:1 row_mask:0xf bank_mask:0xf
	v_fmac_f32_dpp v218, v26, v166 row_shl:15 row_mask:0xf bank_mask:0xf
	v_fmac_f32_dpp v193, v25, v165 row_shl:15 row_mask:0xf bank_mask:0xf
	v_fmac_f32_dpp v218, v10, v162 row_shr:2 row_mask:0xf bank_mask:0xf
	v_fmac_f32_dpp v193, v9, v161 row_shr:2 row_mask:0xf bank_mask:0xf
	v_fmac_f32_dpp v218, v26, v162 row_shl:14 row_mask:0xf bank_mask:0xf
	v_fmac_f32_dpp v193, v25, v161 row_shl:14 row_mask:0xf bank_mask:0xf
	v_fmac_f32_dpp v219, v11, v167 row_shr:1 row_mask:0xf bank_mask:0xf
	v_fmac_f32_dpp v194, v0, v180 row_shr:1 row_mask:0xf bank_mask:0xf
	v_fmac_f32_dpp v219, v27, v167 row_shl:15 row_mask:0xf bank_mask:0xf
	v_fmac_f32_dpp v194, v16, v180 row_shl:15 row_mask:0xf bank_mask:0xf
	v_fmac_f32_dpp v219, v11, v163 row_shr:2 row_mask:0xf bank_mask:0xf
	v_fmac_f32_dpp v194, v0, v176 row_shr:2 row_mask:0xf bank_mask:0xf
	v_fmac_f32_dpp v219, v27, v163 row_shl:14 row_mask:0xf bank_mask:0xf
	v_fmac_f32_dpp v194, v16, v176 row_shl:14 row_mask:0xf bank_mask:0xf
	v_fmac_f32_dpp v220, v2, v182 row_shr:1 row_mask:0xf bank_mask:0xf
	v_fmac_f32_dpp v195, v1, v181 row_shr:1 row_mask:0xf bank_mask:0xf
	v_fmac_f32_dpp v220, v18, v182 row_shl:15 row_mask:0xf bank_mask:0xf
	v_fmac_f32_dpp v195, v17, v181 row_shl:15 row_mask:0xf bank_mask:0xf
	v_fmac_f32_dpp v220, v2, v178 row_shr:2 row_mask:0xf bank_mask:0xf
	v_fmac_f32_dpp v195, v1, v177 row_shr:2 row_mask:0xf bank_mask:0xf
	v_fmac_f32_dpp v220, v18, v178 row_shl:14 row_mask:0xf bank_mask:0xf
	v_fmac_f32_dpp v195, v17, v177 row_shl:14 row_mask:0xf bank_mask:0xf
	v_fmac_f32_dpp v221, v3, v183 row_shr:1 row_mask:0xf bank_mask:0xf
	v_pk_mul_f32 v[216:217], v[192:193], s[34:35]
	v_fmac_f32_dpp v221, v19, v183 row_shl:15 row_mask:0xf bank_mask:0xf
	v_exp_f32_e32 v216, v216
	v_fmac_f32_dpp v221, v3, v179 row_shr:2 row_mask:0xf bank_mask:0xf
	v_exp_f32_e32 v217, v217
	v_fmac_f32_dpp v221, v19, v179 row_shl:14 row_mask:0xf bank_mask:0xf
	v_pk_add_f32 v[216:217], v[216:217], s[36:37]
	v_pk_mul_f32 v[222:223], v[218:219], s[34:35]
	v_rcp_f32_e32 v216, v216
	v_exp_f32_e32 v222, v222
	v_rcp_f32_e32 v217, v217
	v_exp_f32_e32 v223, v223
	v_pk_mul_f32 v[192:193], v[192:193], v[194:195]
	v_pk_add_f32 v[222:223], v[222:223], s[36:37]
	v_pk_mul_f32 v[8:9], v[192:193], v[216:217]
	v_rcp_f32_e32 v222, v222
	v_pk_fma_f32 v[192:193], v[24:25], v[168:169], v[172:173]
	v_rcp_f32_e32 v223, v223
	v_pk_fma_f32 v[194:195], v[16:17], v[184:185], v[188:189]
	v_pk_mul_f32 v[218:219], v[218:219], v[220:221]
	v_fmac_f32_dpp v192, v24, v164 row_shr:1 row_mask:0xf bank_mask:0xf
	v_pk_mul_f32 v[10:11], v[218:219], v[222:223]
	v_fmac_f32_dpp v192, v40, v164 row_shl:15 row_mask:0xf bank_mask:0xf
	v_pk_fma_f32 v[218:219], v[26:27], v[170:171], v[174:175]
	v_fmac_f32_dpp v192, v24, v160 row_shr:2 row_mask:0xf bank_mask:0xf
	v_pk_fma_f32 v[220:221], v[18:19], v[186:187], v[190:191]
	v_fmac_f32_dpp v192, v40, v160 row_shl:14 row_mask:0xf bank_mask:0xf
	v_fmac_f32_dpp v218, v26, v166 row_shr:1 row_mask:0xf bank_mask:0xf
	v_fmac_f32_dpp v193, v25, v165 row_shr:1 row_mask:0xf bank_mask:0xf
	v_fmac_f32_dpp v218, v42, v166 row_shl:15 row_mask:0xf bank_mask:0xf
	v_fmac_f32_dpp v193, v41, v165 row_shl:15 row_mask:0xf bank_mask:0xf
	v_fmac_f32_dpp v218, v26, v162 row_shr:2 row_mask:0xf bank_mask:0xf
	v_fmac_f32_dpp v193, v25, v161 row_shr:2 row_mask:0xf bank_mask:0xf
	v_fmac_f32_dpp v218, v42, v162 row_shl:14 row_mask:0xf bank_mask:0xf
	v_fmac_f32_dpp v193, v41, v161 row_shl:14 row_mask:0xf bank_mask:0xf
	v_fmac_f32_dpp v219, v27, v167 row_shr:1 row_mask:0xf bank_mask:0xf
	v_fmac_f32_dpp v194, v16, v180 row_shr:1 row_mask:0xf bank_mask:0xf
	v_fmac_f32_dpp v219, v43, v167 row_shl:15 row_mask:0xf bank_mask:0xf
	v_fmac_f32_dpp v194, v32, v180 row_shl:15 row_mask:0xf bank_mask:0xf
	v_fmac_f32_dpp v219, v27, v163 row_shr:2 row_mask:0xf bank_mask:0xf
	v_fmac_f32_dpp v194, v16, v176 row_shr:2 row_mask:0xf bank_mask:0xf
	v_fmac_f32_dpp v219, v43, v163 row_shl:14 row_mask:0xf bank_mask:0xf
	v_fmac_f32_dpp v194, v32, v176 row_shl:14 row_mask:0xf bank_mask:0xf
	v_fmac_f32_dpp v220, v18, v182 row_shr:1 row_mask:0xf bank_mask:0xf
; __device__ __forceinline__ float sigmoidf_(float x) { return __builtin_amdgcn_rcpf(1.0f + __expf(-x)); }
; __device__ __forceinline__ void conv_phase(const Params& p, int layer) {
;     ...
;                 for (int e = 0; e < 8; ++e) {
;                     const float G = wg[0][e] * g2[e] + wg[1][e] * g1[e] + wg[2][e] * g0[e] + bg[e];
;                     const float V = wv[0][e] * v2[e] + wv[1][e] * v1[e] + wv[2][e] * v0[e] + bv[e];
;                     o[e] = G * sigmoidf_(G) * V;
	v_fmac_f32_dpp v195, v17, v181 row_shr:1 row_mask:0xf bank_mask:0xf
	v_fmac_f32_dpp v220, v34, v182 row_shl:15 row_mask:0xf bank_mask:0xf
	v_fmac_f32_dpp v195, v33, v181 row_shl:15 row_mask:0xf bank_mask:0xf
	v_fmac_f32_dpp v220, v18, v178 row_shr:2 row_mask:0xf bank_mask:0xf
	v_fmac_f32_dpp v195, v17, v177 row_shr:2 row_mask:0xf bank_mask:0xf
	v_fmac_f32_dpp v220, v34, v178 row_shl:14 row_mask:0xf bank_mask:0xf
	v_fmac_f32_dpp v195, v33, v177 row_shl:14 row_mask:0xf bank_mask:0xf
	v_fmac_f32_dpp v221, v19, v183 row_shr:1 row_mask:0xf bank_mask:0xf
	v_pk_mul_f32 v[216:217], v[192:193], s[34:35]
	v_fmac_f32_dpp v221, v35, v183 row_shl:15 row_mask:0xf bank_mask:0xf
	v_exp_f32_e32 v216, v216
	v_fmac_f32_dpp v221, v19, v179 row_shr:2 row_mask:0xf bank_mask:0xf
	v_exp_f32_e32 v217, v217
	v_fmac_f32_dpp v221, v35, v179 row_shl:14 row_mask:0xf bank_mask:0xf
	v_pk_add_f32 v[216:217], v[216:217], s[36:37]
	v_pk_mul_f32 v[222:223], v[218:219], s[34:35]
	v_rcp_f32_e32 v216, v216
	v_exp_f32_e32 v222, v222
	v_rcp_f32_e32 v217, v217
	v_exp_f32_e32 v223, v223
	v_pk_mul_f32 v[192:193], v[192:193], v[194:195]
	v_pk_add_f32 v[222:223], v[222:223], s[36:37]
	v_pk_mul_f32 v[24:25], v[192:193], v[216:217]
	v_rcp_f32_e32 v222, v222
	v_pk_fma_f32 v[192:193], v[40:41], v[168:169], v[172:173]
	v_rcp_f32_e32 v223, v223
	v_pk_fma_f32 v[194:195], v[32:33], v[184:185], v[188:189]
	v_pk_mul_f32 v[218:219], v[218:219], v[220:221]
	v_fmac_f32_dpp v192, v40, v164 row_shr:1 row_mask:0xf bank_mask:0xf
	v_pk_mul_f32 v[26:27], v[218:219], v[222:223]
	v_fmac_f32_dpp v192, v56, v164 row_shl:15 row_mask:0xf bank_mask:0xf
	v_pk_fma_f32 v[218:219], v[42:43], v[170:171], v[174:175]
	v_fmac_f32_dpp v192, v40, v160 row_shr:2 row_mask:0xf bank_mask:0xf
	v_pk_fma_f32 v[220:221], v[34:35], v[186:187], v[190:191]
	v_fmac_f32_dpp v192, v56, v160 row_shl:14 row_mask:0xf bank_mask:0xf
	v_fmac_f32_dpp v218, v42, v166 row_shr:1 row_mask:0xf bank_mask:0xf
	v_fmac_f32_dpp v193, v41, v165 row_shr:1 row_mask:0xf bank_mask:0xf
	v_fmac_f32_dpp v218, v58, v166 row_shl:15 row_mask:0xf bank_mask:0xf
	v_fmac_f32_dpp v193, v57, v165 row_shl:15 row_mask:0xf bank_mask:0xf
	v_fmac_f32_dpp v218, v42, v162 row_shr:2 row_mask:0xf bank_mask:0xf
	v_fmac_f32_dpp v193, v41, v161 row_shr:2 row_mask:0xf bank_mask:0xf
	v_fmac_f32_dpp v218, v58, v162 row_shl:14 row_mask:0xf bank_mask:0xf
	v_fmac_f32_dpp v193, v57, v161 row_shl:14 row_mask:0xf bank_mask:0xf
	v_fmac_f32_dpp v219, v43, v167 row_shr:1 row_mask:0xf bank_mask:0xf
	v_fmac_f32_dpp v194, v32, v180 row_shr:1 row_mask:0xf bank_mask:0xf
	v_fmac_f32_dpp v219, v59, v167 row_shl:15 row_mask:0xf bank_mask:0xf
	v_fmac_f32_dpp v194, v48, v180 row_shl:15 row_mask:0xf bank_mask:0xf
	v_fmac_f32_dpp v219, v43, v163 row_shr:2 row_mask:0xf bank_mask:0xf
	v_fmac_f32_dpp v194, v32, v176 row_shr:2 row_mask:0xf bank_mask:0xf
	v_fmac_f32_dpp v219, v59, v163 row_shl:14 row_mask:0xf bank_mask:0xf
	v_fmac_f32_dpp v194, v48, v176 row_shl:14 row_mask:0xf bank_mask:0xf
	v_fmac_f32_dpp v220, v34, v182 row_shr:1 row_mask:0xf bank_mask:0xf
	v_fmac_f32_dpp v195, v33, v181 row_shr:1 row_mask:0xf bank_mask:0xf
	v_fmac_f32_dpp v220, v50, v182 row_shl:15 row_mask:0xf bank_mask:0xf
	v_fmac_f32_dpp v195, v49, v181 row_shl:15 row_mask:0xf bank_mask:0xf
	v_fmac_f32_dpp v220, v34, v178 row_shr:2 row_mask:0xf bank_mask:0xf
	v_fmac_f32_dpp v195, v33, v177 row_shr:2 row_mask:0xf bank_mask:0xf
	v_fmac_f32_dpp v220, v50, v178 row_shl:14 row_mask:0xf bank_mask:0xf
	v_fmac_f32_dpp v195, v49, v177 row_shl:14 row_mask:0xf bank_mask:0xf
	v_fmac_f32_dpp v221, v35, v183 row_shr:1 row_mask:0xf bank_mask:0xf
	v_pk_mul_f32 v[216:217], v[192:193], s[34:35]
	v_fmac_f32_dpp v221, v51, v183 row_shl:15 row_mask:0xf bank_mask:0xf
	v_exp_f32_e32 v216, v216
	v_fmac_f32_dpp v221, v35, v179 row_shr:2 row_mask:0xf bank_mask:0xf
	v_exp_f32_e32 v217, v217
	v_fmac_f32_dpp v221, v51, v179 row_shl:14 row_mask:0xf bank_mask:0xf
	v_pk_add_f32 v[216:217], v[216:217], s[36:37]
	v_pk_mul_f32 v[222:223], v[218:219], s[34:35]
	v_rcp_f32_e32 v216, v216
	v_exp_f32_e32 v222, v222
	v_rcp_f32_e32 v217, v217
	v_exp_f32_e32 v223, v223
	v_pk_mul_f32 v[192:193], v[192:193], v[194:195]
	v_pk_add_f32 v[222:223], v[222:223], s[36:37]
	v_pk_mul_f32 v[40:41], v[192:193], v[216:217]
	v_rcp_f32_e32 v222, v222
	v_pk_fma_f32 v[192:193], v[56:57], v[168:169], v[172:173]
	v_rcp_f32_e32 v223, v223
	v_pk_fma_f32 v[194:195], v[48:49], v[184:185], v[188:189]
	v_pk_mul_f32 v[218:219], v[218:219], v[220:221]
	v_fmac_f32_dpp v192, v56, v164 row_shr:1 row_mask:0xf bank_mask:0xf
	v_pk_mul_f32 v[42:43], v[218:219], v[222:223]
	v_fmac_f32_dpp v192, v56, v164 row_shl:15 row_mask:0xf bank_mask:0xf
	v_pk_fma_f32 v[218:219], v[58:59], v[170:171], v[174:175]
	v_fmac_f32_dpp v192, v56, v160 row_shr:2 row_mask:0xf bank_mask:0xf
; __device__ __forceinline__ u32x4 pack8(f32x4 a, f32x4 b) { u32x4 w; w.x = pk2(a[0], a[1]); w.y = pk2(a[2], a[3]); w.z = pk2(b[0], b[1]); w.w = pk2(b[2], b[3]); return w; }
; __device__ __forceinline__ float sigmoidf_(float x) { return __builtin_amdgcn_rcpf(1.0f + __expf(-x)); }
;     __device__ __forceinline__ void operator()(const f32x4 (&acc)[2][2][4][2], const Unit& u, int wr, int wc, int fr, int fq) const {
;     ...
;                     } else if (mode == E_ST16) {
;                         *(u32x4*)((h16*)(ws + F_U16) + (size_t)rowl * 5632 + col) = pack8(v0, v1);
; __device__ __forceinline__ void conv_phase(const Params& p, int layer) {
;     ...
;                 for (int e = 0; e < 8; ++e) {
;                     const float G = wg[0][e] * g2[e] + wg[1][e] * g1[e] + wg[2][e] * g0[e] + bg[e];
;                     const float V = wv[0][e] * v2[e] + wv[1][e] * v1[e] + wv[2][e] * v0[e] + bv[e];
;                     o[e] = G * sigmoidf_(G) * V;
;                     g2[e] = g1[e]; g1[e] = g0[e]; v2[e] = v1[e]; v1[e] = v0[e];
;                 }
;                 *(u32x4*)(act + (size_t)(r0 + i0 + i) * DFF + f) = pack8((f32x4){o[0], o[1], o[2], o[3]}, (f32x4){o[4], o[5], o[6], o[7]});
	v_pk_fma_f32 v[220:221], v[50:51], v[186:187], v[190:191]
	v_fmac_f32_dpp v192, v56, v160 row_shl:14 row_mask:0xf bank_mask:0xf
	v_fmac_f32_dpp v218, v58, v166 row_shr:1 row_mask:0xf bank_mask:0xf
	v_fmac_f32_dpp v193, v57, v165 row_shr:1 row_mask:0xf bank_mask:0xf
	v_fmac_f32_dpp v218, v58, v166 row_shl:15 row_mask:0xf bank_mask:0xf
	v_fmac_f32_dpp v193, v57, v165 row_shl:15 row_mask:0xf bank_mask:0xf
	v_fmac_f32_dpp v218, v58, v162 row_shr:2 row_mask:0xf bank_mask:0xf
	v_fmac_f32_dpp v193, v57, v161 row_shr:2 row_mask:0xf bank_mask:0xf
	v_fmac_f32_dpp v218, v58, v162 row_shl:14 row_mask:0xf bank_mask:0xf
	v_fmac_f32_dpp v193, v57, v161 row_shl:14 row_mask:0xf bank_mask:0xf
	v_fmac_f32_dpp v219, v59, v167 row_shr:1 row_mask:0xf bank_mask:0xf
	v_fmac_f32_dpp v194, v48, v180 row_shr:1 row_mask:0xf bank_mask:0xf
	v_fmac_f32_dpp v219, v59, v167 row_shl:15 row_mask:0xf bank_mask:0xf
	v_fmac_f32_dpp v194, v48, v180 row_shl:15 row_mask:0xf bank_mask:0xf
	v_fmac_f32_dpp v219, v59, v163 row_shr:2 row_mask:0xf bank_mask:0xf
	v_fmac_f32_dpp v194, v48, v176 row_shr:2 row_mask:0xf bank_mask:0xf
	v_fmac_f32_dpp v219, v59, v163 row_shl:14 row_mask:0xf bank_mask:0xf
	v_fmac_f32_dpp v194, v48, v176 row_shl:14 row_mask:0xf bank_mask:0xf
	v_fmac_f32_dpp v220, v50, v182 row_shr:1 row_mask:0xf bank_mask:0xf
	v_fmac_f32_dpp v195, v49, v181 row_shr:1 row_mask:0xf bank_mask:0xf
	v_fmac_f32_dpp v220, v50, v182 row_shl:15 row_mask:0xf bank_mask:0xf
	v_fmac_f32_dpp v195, v49, v181 row_shl:15 row_mask:0xf bank_mask:0xf
	v_fmac_f32_dpp v220, v50, v178 row_shr:2 row_mask:0xf bank_mask:0xf
	v_fmac_f32_dpp v195, v49, v177 row_shr:2 row_mask:0xf bank_mask:0xf
	v_fmac_f32_dpp v220, v50, v178 row_shl:14 row_mask:0xf bank_mask:0xf
	v_fmac_f32_dpp v195, v49, v177 row_shl:14 row_mask:0xf bank_mask:0xf
	v_fmac_f32_dpp v221, v51, v183 row_shr:1 row_mask:0xf bank_mask:0xf
	v_pk_mul_f32 v[216:217], v[192:193], s[34:35]
	v_fmac_f32_dpp v221, v51, v183 row_shl:15 row_mask:0xf bank_mask:0xf
	v_exp_f32_e32 v216, v216
	v_fmac_f32_dpp v221, v51, v179 row_shr:2 row_mask:0xf bank_mask:0xf
	v_exp_f32_e32 v217, v217
	v_fmac_f32_dpp v221, v51, v179 row_shl:14 row_mask:0xf bank_mask:0xf
	v_pk_add_f32 v[216:217], v[216:217], s[36:37]
	v_pk_mul_f32 v[222:223], v[218:219], s[34:35]
	v_rcp_f32_e32 v216, v216
	v_exp_f32_e32 v222, v222
	v_rcp_f32_e32 v217, v217
	v_exp_f32_e32 v223, v223
	v_pk_mul_f32 v[192:193], v[192:193], v[194:195]
	v_pk_add_f32 v[222:223], v[222:223], s[36:37]
	v_pk_mul_f32 v[56:57], v[192:193], v[216:217]
	v_rcp_f32_e32 v222, v222
	v_rcp_f32_e32 v223, v223
	v_pk_mul_f32 v[218:219], v[218:219], v[220:221]
	s_nop 0
	v_pk_mul_f32 v[58:59], v[218:219], v[222:223]
	v_readlane_b32 s0, v250, 38
	v_readlane_b32 s1, v250, 39
	s_movk_i32 s33, 0x1600
	v_lshl_add_u32 v220, v202, 1, s27
	v_mov_b32_e32 v221, v197
	v_mad_u64_u32 v[216:217], s[38:39], v240, s33, v[220:221]
	s_mov_b32 s34, 0x16000
	s_mov_b32 s35, 0
	s_mov_b32 s36, 0x6e000
	s_mov_b32 s37, 0
	v_lshl_add_u64 v[216:217], s[0:1], 0, v[216:217]
	v_cvt_pk_f16_f32 v112, v124, v125
	v_cvt_pk_f16_f32 v113, v126, v127
	v_cvt_pk_f16_f32 v114, v120, v121
	v_cvt_pk_f16_f32 v115, v122, v123
	v_lshl_add_u64 v[218:219], v[216:217], 0, s[34:35]
	global_store_dwordx4 v[216:217], v[112:115], off
	v_cvt_pk_f16_f32 v96, v108, v109
	v_cvt_pk_f16_f32 v97, v110, v111
	v_cvt_pk_f16_f32 v98, v104, v105
	v_cvt_pk_f16_f32 v99, v106, v107
	v_lshl_add_u64 v[216:217], v[218:219], 0, s[34:35]
	global_store_dwordx4 v[218:219], v[96:99], off
	v_cvt_pk_f16_f32 v80, v92, v93
	v_cvt_pk_f16_f32 v81, v94, v95
	v_cvt_pk_f16_f32 v82, v88, v89
	v_cvt_pk_f16_f32 v83, v90, v91
	v_lshl_add_u64 v[218:219], v[216:217], 0, s[34:35]
	global_store_dwordx4 v[216:217], v[80:83], off
	v_cvt_pk_f16_f32 v64, v76, v77
	v_cvt_pk_f16_f32 v65, v78, v79
	v_cvt_pk_f16_f32 v66, v72, v73
	v_cvt_pk_f16_f32 v67, v74, v75
	v_lshl_add_u64 v[216:217], v[218:219], 0, s[36:37]
	global_store_dwordx4 v[218:219], v[64:67], off
	v_cvt_pk_f16_f32 v48, v60, v61
	v_cvt_pk_f16_f32 v49, v62, v63
	v_cvt_pk_f16_f32 v50, v56, v57
	v_cvt_pk_f16_f32 v51, v58, v59
	v_lshl_add_u64 v[218:219], v[216:217], 0, s[34:35]
	global_store_dwordx4 v[216:217], v[48:51], off
	v_cvt_pk_f16_f32 v32, v44, v45
	v_cvt_pk_f16_f32 v33, v46, v47
	v_cvt_pk_f16_f32 v34, v40, v41
	v_cvt_pk_f16_f32 v35, v42, v43
	v_lshl_add_u64 v[216:217], v[218:219], 0, s[34:35]
	global_store_dwordx4 v[218:219], v[32:35], off
	v_cvt_pk_f16_f32 v16, v28, v29
	v_cvt_pk_f16_f32 v17, v30, v31
	v_cvt_pk_f16_f32 v18, v24, v25
	v_cvt_pk_f16_f32 v19, v26, v27
	v_lshl_add_u64 v[218:219], v[216:217], 0, s[34:35]
	global_store_dwordx4 v[216:217], v[16:19], off
	v_cvt_pk_f16_f32 v0, v12, v13
	v_cvt_pk_f16_f32 v1, v14, v15
	v_cvt_pk_f16_f32 v2, v8, v9
	v_cvt_pk_f16_f32 v3, v10, v11
	global_store_dwordx4 v[218:219], v[0:3], off
